# LDS-DMA loads in GEMM K-loops use SGPR base + 32-bit VGPR offset (no per-load 64-bit VALU add)
# baseline (speedup 1.0000x reference)
; #define PG8_STAGE(bufoff, gbase, voff) do { _Pragma("unroll") for (int _i = 0; _i < 2; ++_i) \
;         __builtin_amdgcn_global_load_lds((const unsigned*)((const char*)(gbase) + (voff)[_i]), (LAS unsigned*)(lds + (bufoff) + ldsw + _i * 8192), 16, 0, 0); } while (0)
; #define PG8_LDA(dst, b, h) do { _Pragma("unroll") for (int m = 0; m < 4; ++m) _Pragma("unroll") for (int k = 0; k < 2; ++k) dst[m][k] = *(const LAS bf16x8*)(lds + PG8_SA(b, h) + aoff + m * 2048 + k * 1024); } while (0)
; #define PG8_LDB(dst, b, h) do { _Pragma("unroll") for (int n = 0; n < 2; ++n) _Pragma("unroll") for (int k = 0; k < 2; ++k) dst[n][k] = *(const LAS bf16x8*)(lds + PG8_SB(b, h) + boff + n * 2048 + k * 1024); } while (0)
; #define PG8_MMA(ai, bj, At, Bt) do { __builtin_amdgcn_s_setprio(1); _Pragma("unroll") for (int m = 0; m < 4; ++m) _Pragma("unroll") for (int n = 0; n < 2; ++n) _Pragma("unroll") for (int k = 0; k < 2; ++k) \
;         acc[ai][bj][m][n] = __builtin_amdgcn_mfma_f32_16x16x32_bf16(Bt[n][k], At[m][k], acc[ai][bj][m][n], 0, 0, 0); __builtin_amdgcn_s_setprio(0); } while (0)
; #define PG8_WAIT_V(n) asm volatile("s_waitcnt vmcnt(" #n ")" ::: "memory")
; #define PG8_WAIT_L(n) asm volatile("s_waitcnt lgkmcnt(" #n ")" ::: "memory")
; #define PG8_BAR __builtin_amdgcn_s_barrier()
; #define PG8_SCHED __builtin_amdgcn_sched_barrier(0)
; DI void gemm_phase(LAS unsigned char* lds, const Gemm g, const StaticOrder& S, const Epi& E) {
;     ...
;         for (int t = 0; t < nt; t += 2) {
;             const bool last = (t == nt - 2);
;             const char* a1 = cA + (size_t)(t + 1) * kstep;
;             const char* a2 = last ? nA : cA + (size_t)(t + 2) * kstep; const char* b2 = last ? nB : cB + (size_t)(t + 2) * kstep;
;             const char* a3 = a2 + kstep; const char* b3 = b2 + kstep;
;             PG8_LDB(B0, 0, 0); PG8_LDB(B1, 0, 1); PG8_SCHED; PG8_LDA(At, 0, 0); PG8_STAGE(PG8_SA(1, 1), a1 + hsA, voffA);
;             PG8_WAIT_V(8); PG8_WAIT_L(0); PG8_BAR; PG8_MMA(0, 0, At, B0); PG8_MMA(0, 1, At, B1); PG8_BAR; PG8_SCHED;
;             PG8_LDA(At, 0, 1); PG8_STAGE(PG8_SB(0, 0), b2, voffB); PG8_STAGE(PG8_SB(0, 1), b2 + hsB, voffB); PG8_STAGE(PG8_SA(0, 0), a2, voffA);
;             PG8_WAIT_V(8); PG8_WAIT_L(0); PG8_BAR; PG8_MMA(1, 0, At, B0); PG8_MMA(1, 1, At, B1); PG8_BAR; PG8_SCHED;
.LBB0_177:
	ds_read_b128 v[152:155], v149
	ds_read_b128 v[156:159], v149 offset:1024
	ds_read_b128 v[160:163], v149 offset:2048
	ds_read_b128 v[170:173], v149 offset:3072
	ds_read_b128 v[174:177], v150
	ds_read_b128 v[178:181], v150 offset:1024
	ds_read_b128 v[182:185], v150 offset:2048
	ds_read_b128 v[186:189], v150 offset:3072
	s_add_u32 s34, s30, 0xfff80080
	s_addc_u32 s35, s31, -1
	s_cmp_eq_u32 s56, 28
	s_cselect_b32 s39, s5, s35
	s_cselect_b32 s38, s23, s34
	s_cselect_b32 s35, s21, s55
	s_cselect_b32 s34, s29, s54
	s_add_i32 m0, s13, 0xc000
	ds_read_b128 v[190:193], v151
	ds_read_b128 v[194:197], v151 offset:1024
	ds_read_b128 v[198:201], v151 offset:2048
	ds_read_b128 v[202:205], v151 offset:3072
	ds_read_b128 v[206:209], v151 offset:4096
	ds_read_b128 v[210:213], v151 offset:5120
	ds_read_b128 v[214:217], v151 offset:6144
	ds_read_b128 v[218:221], v151 offset:7168
	global_load_lds_dwordx4 v136, s[30:31]
	s_add_i32 m0, s13, 0xe000
	s_nop 0
	global_load_lds_dwordx4 v138, s[30:31]
	s_waitcnt vmcnt(8)
	s_waitcnt lgkmcnt(0)
	s_barrier
	s_setprio 1
	s_waitcnt lgkmcnt(0)
	v_mfma_f32_16x16x32_bf16 v[124:127], v[152:155], v[190:193], v[124:127]
	v_mfma_f32_16x16x32_bf16 v[124:127], v[156:159], v[194:197], v[124:127]
	v_mfma_f32_16x16x32_bf16 v[120:123], v[170:173], v[194:197], v[120:123]
	v_mfma_f32_16x16x32_bf16 v[120:123], v[160:163], v[190:193], v[120:123]
	v_mfma_f32_16x16x32_bf16 v[108:111], v[160:163], v[198:201], v[108:111]
	v_mfma_f32_16x16x32_bf16 v[108:111], v[170:173], v[202:205], v[108:111]
	v_mfma_f32_16x16x32_bf16 v[116:119], v[156:159], v[202:205], v[116:119]
	v_mfma_f32_16x16x32_bf16 v[116:119], v[152:155], v[198:201], v[116:119]
	v_mfma_f32_16x16x32_bf16 v[100:103], v[152:155], v[206:209], v[100:103]
	v_mfma_f32_16x16x32_bf16 v[100:103], v[156:159], v[210:213], v[100:103]
	v_mfma_f32_16x16x32_bf16 v[92:95], v[170:173], v[210:213], v[92:95]
	v_mfma_f32_16x16x32_bf16 v[92:95], v[160:163], v[206:209], v[92:95]
	v_mfma_f32_16x16x32_bf16 v[76:79], v[160:163], v[214:217], v[76:79]
	v_mfma_f32_16x16x32_bf16 v[76:79], v[170:173], v[218:221], v[76:79]
	v_mfma_f32_16x16x32_bf16 v[84:87], v[156:159], v[218:221], v[84:87]
	v_mfma_f32_16x16x32_bf16 v[84:87], v[152:155], v[214:217], v[84:87]
	s_setprio 0
	s_setprio 1
	v_mfma_f32_16x16x32_bf16 v[112:115], v[174:177], v[190:193], v[112:115]
	v_mfma_f32_16x16x32_bf16 v[112:115], v[178:181], v[194:197], v[112:115]
	v_mfma_f32_16x16x32_bf16 v[104:107], v[186:189], v[194:197], v[104:107]
	v_mfma_f32_16x16x32_bf16 v[104:107], v[182:185], v[190:193], v[104:107]
	v_mfma_f32_16x16x32_bf16 v[88:91], v[182:185], v[198:201], v[88:91]
	v_mfma_f32_16x16x32_bf16 v[88:91], v[186:189], v[202:205], v[88:91]
	v_mfma_f32_16x16x32_bf16 v[96:99], v[178:181], v[202:205], v[96:99]
	v_mfma_f32_16x16x32_bf16 v[96:99], v[174:177], v[198:201], v[96:99]
	v_mfma_f32_16x16x32_bf16 v[80:83], v[174:177], v[206:209], v[80:83]
	v_mfma_f32_16x16x32_bf16 v[80:83], v[178:181], v[210:213], v[80:83]
	v_mfma_f32_16x16x32_bf16 v[72:75], v[186:189], v[210:213], v[72:75]
	v_mfma_f32_16x16x32_bf16 v[72:75], v[182:185], v[206:209], v[72:75]
	v_mfma_f32_16x16x32_bf16 v[64:67], v[182:185], v[214:217], v[64:67]
	v_mfma_f32_16x16x32_bf16 v[64:67], v[186:189], v[218:221], v[64:67]
	v_mfma_f32_16x16x32_bf16 v[68:71], v[178:181], v[218:221], v[68:71]
	v_mfma_f32_16x16x32_bf16 v[68:71], v[174:177], v[214:217], v[68:71]
	s_setprio 0
	s_barrier
	s_add_i32 s46, s50, s12
	s_add_u32 s98, s34, 0x80
	s_addc_u32 s99, s35, 0
	s_mov_b32 m0, s46
	ds_read_b128 v[190:193], v151 offset:16384
	ds_read_b128 v[194:197], v151 offset:17408
	ds_read_b128 v[198:201], v151 offset:18432
	ds_read_b128 v[202:205], v151 offset:19456
	ds_read_b128 v[206:209], v151 offset:20480
	ds_read_b128 v[210:213], v151 offset:21504
	ds_read_b128 v[214:217], v151 offset:22528
	ds_read_b128 v[218:221], v151 offset:23552
	global_load_lds_dwordx4 v130, s[34:35]
	s_add_i32 m0, s46, 0x2000
	s_add_u32 s46, s34, 0x80000
	s_addc_u32 s47, s35, 0
	s_add_i32 s57, s51, s12
	global_load_lds_dwordx4 v134, s[34:35]
	s_mov_b32 m0, s57
	s_nop 0
	global_load_lds_dwordx4 v130, s[46:47]
	s_add_i32 m0, s57, 0x2000
	s_nop 0
	global_load_lds_dwordx4 v134, s[46:47]
	s_add_u32 s100, s38, 0x80
	s_addc_u32 s101, s39, 0
	s_mov_b32 m0, s13
	s_nop 0
	global_load_lds_dwordx4 v128, s[38:39]
	s_mov_b32 m0, s33
	s_nop 0
	global_load_lds_dwordx4 v132, s[38:39]
	s_waitcnt vmcnt(8)
	s_waitcnt lgkmcnt(0)
	s_barrier
	s_setprio 1
	s_waitcnt lgkmcnt(0)
	v_mfma_f32_16x16x32_bf16 v[60:63], v[152:155], v[190:193], v[60:63]
	v_mfma_f32_16x16x32_bf16 v[60:63], v[156:159], v[194:197], v[60:63]
	v_mfma_f32_16x16x32_bf16 v[56:59], v[170:173], v[194:197], v[56:59]
	v_mfma_f32_16x16x32_bf16 v[56:59], v[160:163], v[190:193], v[56:59]
	v_mfma_f32_16x16x32_bf16 v[44:47], v[160:163], v[198:201], v[44:47]
	v_mfma_f32_16x16x32_bf16 v[44:47], v[170:173], v[202:205], v[44:47]
	v_mfma_f32_16x16x32_bf16 v[52:55], v[156:159], v[202:205], v[52:55]
	v_mfma_f32_16x16x32_bf16 v[52:55], v[152:155], v[198:201], v[52:55]
	v_mfma_f32_16x16x32_bf16 v[36:39], v[152:155], v[206:209], v[36:39]
	v_mfma_f32_16x16x32_bf16 v[36:39], v[156:159], v[210:213], v[36:39]
	v_mfma_f32_16x16x32_bf16 v[28:31], v[170:173], v[210:213], v[28:31]
	v_mfma_f32_16x16x32_bf16 v[28:31], v[160:163], v[206:209], v[28:31]
	v_mfma_f32_16x16x32_bf16 v[12:15], v[160:163], v[214:217], v[12:15]
	v_mfma_f32_16x16x32_bf16 v[12:15], v[170:173], v[218:221], v[12:15]
	v_mfma_f32_16x16x32_bf16 v[20:23], v[156:159], v[218:221], v[20:23]
	v_mfma_f32_16x16x32_bf16 v[20:23], v[152:155], v[214:217], v[20:23]
	s_setprio 0
	s_setprio 1
	v_mfma_f32_16x16x32_bf16 v[48:51], v[174:177], v[190:193], v[48:51]
	v_mfma_f32_16x16x32_bf16 v[48:51], v[178:181], v[194:197], v[48:51]
	v_mfma_f32_16x16x32_bf16 v[40:43], v[186:189], v[194:197], v[40:43]
	v_mfma_f32_16x16x32_bf16 v[40:43], v[182:185], v[190:193], v[40:43]
	v_mfma_f32_16x16x32_bf16 v[24:27], v[182:185], v[198:201], v[24:27]
	v_mfma_f32_16x16x32_bf16 v[24:27], v[186:189], v[202:205], v[24:27]
	v_mfma_f32_16x16x32_bf16 v[32:35], v[178:181], v[202:205], v[32:35]
	v_mfma_f32_16x16x32_bf16 v[32:35], v[174:177], v[198:201], v[32:35]
	v_mfma_f32_16x16x32_bf16 v[16:19], v[174:177], v[206:209], v[16:19]
	v_mfma_f32_16x16x32_bf16 v[16:19], v[178:181], v[210:213], v[16:19]
	v_mfma_f32_16x16x32_bf16 v[8:11], v[186:189], v[210:213], v[8:11]
	v_mfma_f32_16x16x32_bf16 v[8:11], v[182:185], v[206:209], v[8:11]
	v_mfma_f32_16x16x32_bf16 v[0:3], v[182:185], v[214:217], v[0:3]
	v_mfma_f32_16x16x32_bf16 v[0:3], v[186:189], v[218:221], v[0:3]
	v_mfma_f32_16x16x32_bf16 v[4:7], v[178:181], v[218:221], v[4:7]
	v_mfma_f32_16x16x32_bf16 v[4:7], v[174:177], v[214:217], v[4:7]
	s_setprio 0
	s_barrier
; #define PG8_STAGE(bufoff, gbase, voff) do { _Pragma("unroll") for (int _i = 0; _i < 2; ++_i) \
;         __builtin_amdgcn_global_load_lds((const unsigned*)((const char*)(gbase) + (voff)[_i]), (LAS unsigned*)(lds + (bufoff) + ldsw + _i * 8192), 16, 0, 0); } while (0)
; #define PG8_LDA(dst, b, h) do { _Pragma("unroll") for (int m = 0; m < 4; ++m) _Pragma("unroll") for (int k = 0; k < 2; ++k) dst[m][k] = *(const LAS bf16x8*)(lds + PG8_SA(b, h) + aoff + m * 2048 + k * 1024); } while (0)
; #define PG8_LDB(dst, b, h) do { _Pragma("unroll") for (int n = 0; n < 2; ++n) _Pragma("unroll") for (int k = 0; k < 2; ++k) dst[n][k] = *(const LAS bf16x8*)(lds + PG8_SB(b, h) + boff + n * 2048 + k * 1024); } while (0)
; #define PG8_MMA(ai, bj, At, Bt) do { __builtin_amdgcn_s_setprio(1); _Pragma("unroll") for (int m = 0; m < 4; ++m) _Pragma("unroll") for (int n = 0; n < 2; ++n) _Pragma("unroll") for (int k = 0; k < 2; ++k) \
;         acc[ai][bj][m][n] = __builtin_amdgcn_mfma_f32_16x16x32_bf16(Bt[n][k], At[m][k], acc[ai][bj][m][n], 0, 0, 0); __builtin_amdgcn_s_setprio(0); } while (0)
; #define PG8_WAIT_V(n) asm volatile("s_waitcnt vmcnt(" #n ")" ::: "memory")
; #define PG8_WAIT_L(n) asm volatile("s_waitcnt lgkmcnt(" #n ")" ::: "memory")
; #define PG8_BAR __builtin_amdgcn_s_barrier()
; #define PG8_SCHED __builtin_amdgcn_sched_barrier(0)
; DI void gemm_phase(LAS unsigned char* lds, const Gemm g, const StaticOrder& S, const Epi& E) {
;     ...
;             PG8_LDB(B0, 1, 0); PG8_LDB(B1, 1, 1); PG8_SCHED; PG8_LDA(At, 1, 0); PG8_STAGE(PG8_SA(0, 1), a2 + hsA, voffA);
;             PG8_WAIT_V(8); PG8_WAIT_L(0); PG8_BAR; PG8_MMA(0, 0, At, B0); PG8_MMA(0, 1, At, B1); PG8_BAR; PG8_SCHED;
;             PG8_LDA(At, 1, 1); PG8_STAGE(PG8_SB(1, 0), b3, voffB); PG8_STAGE(PG8_SB(1, 1), b3 + hsB, voffB); PG8_STAGE(PG8_SA(1, 0), a3, voffA);
;             PG8_WAIT_V(8); PG8_WAIT_L(0); PG8_BAR; PG8_MMA(1, 0, At, B0); PG8_MMA(1, 1, At, B1); PG8_BAR; PG8_SCHED;
;         }
;         if (wr == 0) PG8_BAR;
	s_add_i32 s46, 0, 0x18000
	v_add_u32_e32 v166, s46, v147
	s_add_i32 s47, 0, 0x1c000
	ds_read_b128 v[152:155], v166
	ds_read_b128 v[156:159], v166 offset:1024
	ds_read_b128 v[160:163], v166 offset:2048
	ds_read_b128 v[170:173], v166 offset:3072
	v_add_u32_e32 v166, s47, v147
	ds_read_b128 v[174:177], v166
	ds_read_b128 v[178:181], v166 offset:1024
	ds_read_b128 v[182:185], v166 offset:2048
	ds_read_b128 v[186:189], v166 offset:3072
	s_add_u32 s38, s38, 0x80000
	s_addc_u32 s39, s39, 0
	s_mov_b32 m0, s40
	ds_read_b128 v[190:193], v151 offset:32768
	ds_read_b128 v[194:197], v151 offset:33792
	ds_read_b128 v[198:201], v151 offset:34816
	ds_read_b128 v[202:205], v151 offset:35840
	ds_read_b128 v[206:209], v151 offset:36864
	ds_read_b128 v[210:213], v151 offset:37888
	ds_read_b128 v[214:217], v151 offset:38912
	ds_read_b128 v[218:221], v151 offset:39936
	global_load_lds_dwordx4 v128, s[38:39]
	s_mov_b32 m0, s41
	s_nop 0
	global_load_lds_dwordx4 v132, s[38:39]
	s_waitcnt vmcnt(8)
	s_waitcnt lgkmcnt(0)
	s_barrier
	s_setprio 1
	s_waitcnt lgkmcnt(0)
	v_mfma_f32_16x16x32_bf16 v[124:127], v[152:155], v[190:193], v[124:127]
	v_mfma_f32_16x16x32_bf16 v[124:127], v[156:159], v[194:197], v[124:127]
	v_mfma_f32_16x16x32_bf16 v[120:123], v[170:173], v[194:197], v[120:123]
	v_mfma_f32_16x16x32_bf16 v[120:123], v[160:163], v[190:193], v[120:123]
	v_mfma_f32_16x16x32_bf16 v[108:111], v[160:163], v[198:201], v[108:111]
	v_mfma_f32_16x16x32_bf16 v[108:111], v[170:173], v[202:205], v[108:111]
	v_mfma_f32_16x16x32_bf16 v[116:119], v[156:159], v[202:205], v[116:119]
	v_mfma_f32_16x16x32_bf16 v[116:119], v[152:155], v[198:201], v[116:119]
	v_mfma_f32_16x16x32_bf16 v[100:103], v[152:155], v[206:209], v[100:103]
	v_mfma_f32_16x16x32_bf16 v[100:103], v[156:159], v[210:213], v[100:103]
	v_mfma_f32_16x16x32_bf16 v[92:95], v[170:173], v[210:213], v[92:95]
	v_mfma_f32_16x16x32_bf16 v[92:95], v[160:163], v[206:209], v[92:95]
	v_mfma_f32_16x16x32_bf16 v[76:79], v[160:163], v[214:217], v[76:79]
	v_mfma_f32_16x16x32_bf16 v[76:79], v[170:173], v[218:221], v[76:79]
	v_mfma_f32_16x16x32_bf16 v[84:87], v[156:159], v[218:221], v[84:87]
	v_mfma_f32_16x16x32_bf16 v[84:87], v[152:155], v[214:217], v[84:87]
	s_setprio 0
	s_setprio 1
	v_mfma_f32_16x16x32_bf16 v[112:115], v[174:177], v[190:193], v[112:115]
	v_mfma_f32_16x16x32_bf16 v[112:115], v[178:181], v[194:197], v[112:115]
	v_mfma_f32_16x16x32_bf16 v[104:107], v[186:189], v[194:197], v[104:107]
	v_mfma_f32_16x16x32_bf16 v[104:107], v[182:185], v[190:193], v[104:107]
	v_mfma_f32_16x16x32_bf16 v[88:91], v[182:185], v[198:201], v[88:91]
	v_mfma_f32_16x16x32_bf16 v[88:91], v[186:189], v[202:205], v[88:91]
	v_mfma_f32_16x16x32_bf16 v[96:99], v[178:181], v[202:205], v[96:99]
	v_mfma_f32_16x16x32_bf16 v[96:99], v[174:177], v[198:201], v[96:99]
	v_mfma_f32_16x16x32_bf16 v[80:83], v[174:177], v[206:209], v[80:83]
	v_mfma_f32_16x16x32_bf16 v[80:83], v[178:181], v[210:213], v[80:83]
	v_mfma_f32_16x16x32_bf16 v[72:75], v[186:189], v[210:213], v[72:75]
	v_mfma_f32_16x16x32_bf16 v[72:75], v[182:185], v[206:209], v[72:75]
	v_mfma_f32_16x16x32_bf16 v[64:67], v[182:185], v[214:217], v[64:67]
	v_mfma_f32_16x16x32_bf16 v[64:67], v[186:189], v[218:221], v[64:67]
	v_mfma_f32_16x16x32_bf16 v[68:71], v[178:181], v[218:221], v[68:71]
	v_mfma_f32_16x16x32_bf16 v[68:71], v[174:177], v[214:217], v[68:71]
	s_setprio 0
	s_barrier
	s_add_i32 s38, s46, s12
	s_mov_b32 m0, s38
	ds_read_b128 v[190:193], v151 offset:49152
	ds_read_b128 v[194:197], v151 offset:50176
	ds_read_b128 v[198:201], v151 offset:51200
	ds_read_b128 v[202:205], v151 offset:52224
	ds_read_b128 v[206:209], v151 offset:53248
	ds_read_b128 v[210:213], v151 offset:54272
	ds_read_b128 v[214:217], v151 offset:55296
	ds_read_b128 v[218:221], v151 offset:56320
	global_load_lds_dwordx4 v130, s[98:99]
	s_add_i32 m0, s38, 0x2000
	s_add_u32 s34, s34, 0x80080
	s_addc_u32 s35, s35, 0
	s_add_i32 s38, s47, s12
	global_load_lds_dwordx4 v134, s[98:99]
	s_mov_b32 m0, s38
	s_nop 0
	global_load_lds_dwordx4 v130, s[34:35]
	s_add_i32 m0, s38, 0x2000
	s_nop 0
	global_load_lds_dwordx4 v134, s[34:35]
	s_mov_b32 m0, s43
	s_nop 0
	global_load_lds_dwordx4 v128, s[100:101]
	s_mov_b32 m0, s48
	s_nop 0
	global_load_lds_dwordx4 v132, s[100:101]
	s_waitcnt vmcnt(8)
	s_waitcnt lgkmcnt(0)
	s_barrier
	s_setprio 1
	s_waitcnt lgkmcnt(0)
	v_mfma_f32_16x16x32_bf16 v[60:63], v[152:155], v[190:193], v[60:63]
	v_mfma_f32_16x16x32_bf16 v[60:63], v[156:159], v[194:197], v[60:63]
	v_mfma_f32_16x16x32_bf16 v[56:59], v[170:173], v[194:197], v[56:59]
	v_mfma_f32_16x16x32_bf16 v[56:59], v[160:163], v[190:193], v[56:59]
	v_mfma_f32_16x16x32_bf16 v[44:47], v[160:163], v[198:201], v[44:47]
	v_mfma_f32_16x16x32_bf16 v[44:47], v[170:173], v[202:205], v[44:47]
	v_mfma_f32_16x16x32_bf16 v[52:55], v[156:159], v[202:205], v[52:55]
	v_mfma_f32_16x16x32_bf16 v[52:55], v[152:155], v[198:201], v[52:55]
	v_mfma_f32_16x16x32_bf16 v[36:39], v[152:155], v[206:209], v[36:39]
	v_mfma_f32_16x16x32_bf16 v[36:39], v[156:159], v[210:213], v[36:39]
	v_mfma_f32_16x16x32_bf16 v[28:31], v[170:173], v[210:213], v[28:31]
	v_mfma_f32_16x16x32_bf16 v[28:31], v[160:163], v[206:209], v[28:31]
	v_mfma_f32_16x16x32_bf16 v[12:15], v[160:163], v[214:217], v[12:15]
	v_mfma_f32_16x16x32_bf16 v[12:15], v[170:173], v[218:221], v[12:15]
	v_mfma_f32_16x16x32_bf16 v[20:23], v[156:159], v[218:221], v[20:23]
	v_mfma_f32_16x16x32_bf16 v[20:23], v[152:155], v[214:217], v[20:23]
	s_setprio 0
	s_setprio 1
	v_mfma_f32_16x16x32_bf16 v[48:51], v[174:177], v[190:193], v[48:51]
	v_mfma_f32_16x16x32_bf16 v[48:51], v[178:181], v[194:197], v[48:51]
	v_mfma_f32_16x16x32_bf16 v[40:43], v[186:189], v[194:197], v[40:43]
	v_mfma_f32_16x16x32_bf16 v[40:43], v[182:185], v[190:193], v[40:43]
	v_mfma_f32_16x16x32_bf16 v[24:27], v[182:185], v[198:201], v[24:27]
	v_mfma_f32_16x16x32_bf16 v[24:27], v[186:189], v[202:205], v[24:27]
	v_mfma_f32_16x16x32_bf16 v[32:35], v[178:181], v[202:205], v[32:35]
	v_mfma_f32_16x16x32_bf16 v[32:35], v[174:177], v[198:201], v[32:35]
	v_mfma_f32_16x16x32_bf16 v[16:19], v[174:177], v[206:209], v[16:19]
	v_mfma_f32_16x16x32_bf16 v[16:19], v[178:181], v[210:213], v[16:19]
	v_mfma_f32_16x16x32_bf16 v[8:11], v[186:189], v[210:213], v[8:11]
	v_mfma_f32_16x16x32_bf16 v[8:11], v[182:185], v[206:209], v[8:11]
	v_mfma_f32_16x16x32_bf16 v[0:3], v[182:185], v[214:217], v[0:3]
	v_mfma_f32_16x16x32_bf16 v[0:3], v[186:189], v[218:221], v[0:3]
	v_mfma_f32_16x16x32_bf16 v[4:7], v[178:181], v[218:221], v[4:7]
	v_mfma_f32_16x16x32_bf16 v[4:7], v[174:177], v[214:217], v[4:7]
	s_setprio 0
	s_barrier
	s_add_i32 s56, s56, 2
	s_add_u32 s30, s30, 0x100
	s_addc_u32 s31, s31, 0
	s_add_u32 s54, s54, 0x100
	s_addc_u32 s55, s55, 0
	s_cmp_gt_u32 s56, 29
	s_cbranch_scc0 .LBB0_177
	s_and_b64 vcc, exec, s[18:19]
	s_cbranch_vccz .LBB0_180
	s_barrier

; #define PG8_STAGE(bufoff, gbase, voff) do { _Pragma("unroll") for (int _i = 0; _i < 2; ++_i) \
;         __builtin_amdgcn_global_load_lds((const unsigned*)((const char*)(gbase) + (voff)[_i]), (LAS unsigned*)(lds + (bufoff) + ldsw + _i * 8192), 16, 0, 0); } while (0)
; #define PG8_LDA(dst, b, h) do { _Pragma("unroll") for (int m = 0; m < 4; ++m) _Pragma("unroll") for (int k = 0; k < 2; ++k) dst[m][k] = *(const LAS bf16x8*)(lds + PG8_SA(b, h) + aoff + m * 2048 + k * 1024); } while (0)
; #define PG8_LDB(dst, b, h) do { _Pragma("unroll") for (int n = 0; n < 2; ++n) _Pragma("unroll") for (int k = 0; k < 2; ++k) dst[n][k] = *(const LAS bf16x8*)(lds + PG8_SB(b, h) + boff + n * 2048 + k * 1024); } while (0)
; #define PG8_MMA(ai, bj, At, Bt) do { __builtin_amdgcn_s_setprio(1); _Pragma("unroll") for (int m = 0; m < 4; ++m) _Pragma("unroll") for (int n = 0; n < 2; ++n) _Pragma("unroll") for (int k = 0; k < 2; ++k) \
;         acc[ai][bj][m][n] = __builtin_amdgcn_mfma_f32_16x16x32_bf16(Bt[n][k], At[m][k], acc[ai][bj][m][n], 0, 0, 0); __builtin_amdgcn_s_setprio(0); } while (0)
; #define PG8_WAIT_V(n) asm volatile("s_waitcnt vmcnt(" #n ")" ::: "memory")
; #define PG8_WAIT_L(n) asm volatile("s_waitcnt lgkmcnt(" #n ")" ::: "memory")
; #define PG8_BAR __builtin_amdgcn_s_barrier()
; #define PG8_SCHED __builtin_amdgcn_sched_barrier(0)
; DI void gemm_phase(LAS unsigned char* lds, const Gemm g, const StaticOrder& S, const Epi& E) {
;     ...
;         for (int t = 0; t < nt; t += 2) {
;             const bool last = (t == nt - 2);
;             const char* a1 = cA + (size_t)(t + 1) * kstep;
;             const char* a2 = last ? nA : cA + (size_t)(t + 2) * kstep; const char* b2 = last ? nB : cB + (size_t)(t + 2) * kstep;
;             const char* a3 = a2 + kstep; const char* b3 = b2 + kstep;
;             PG8_LDB(B0, 0, 0); PG8_LDB(B1, 0, 1); PG8_SCHED; PG8_LDA(At, 0, 0); PG8_STAGE(PG8_SA(1, 1), a1 + hsA, voffA);
;             PG8_WAIT_V(8); PG8_WAIT_L(0); PG8_BAR; PG8_MMA(0, 0, At, B0); PG8_MMA(0, 1, At, B1); PG8_BAR; PG8_SCHED;
;             PG8_LDA(At, 0, 1); PG8_STAGE(PG8_SB(0, 0), b2, voffB); PG8_STAGE(PG8_SB(0, 1), b2 + hsB, voffB); PG8_STAGE(PG8_SA(0, 0), a2, voffA);
;             PG8_WAIT_V(8); PG8_WAIT_L(0); PG8_BAR; PG8_MMA(1, 0, At, B0); PG8_MMA(1, 1, At, B1); PG8_BAR; PG8_SCHED;
.LBB0_343:
	ds_read_b128 v[146:149], v159
	ds_read_b128 v[150:153], v159 offset:1024
	ds_read_b128 v[162:165], v159 offset:2048
	ds_read_b128 v[170:173], v159 offset:3072
	ds_read_b128 v[174:177], v160
	ds_read_b128 v[178:181], v160 offset:1024
	ds_read_b128 v[182:185], v160 offset:2048
	ds_read_b128 v[186:189], v160 offset:3072
	s_add_u32 s4, s34, 0x100
	s_addc_u32 s5, s35, 0
	s_cmp_eq_u32 s70, 4
	s_cselect_b32 s53, s27, s5
	s_cselect_b32 s52, s26, s4
	s_cselect_b32 s51, s25, s69
	s_cselect_b32 s50, s31, s68
	s_add_i32 m0, s13, 0xc000
	ds_read_b128 v[190:193], v161
	ds_read_b128 v[194:197], v161 offset:1024
	ds_read_b128 v[198:201], v161 offset:2048
	ds_read_b128 v[202:205], v161 offset:3072
	ds_read_b128 v[206:209], v161 offset:4096
	ds_read_b128 v[210:213], v161 offset:5120
	ds_read_b128 v[214:217], v161 offset:6144
	ds_read_b128 v[218:221], v161 offset:7168
	global_load_lds_dwordx4 v138, s[34:35]
	s_add_i32 m0, s13, 0xe000
	s_nop 0
	global_load_lds_dwordx4 v140, s[34:35]
	s_waitcnt vmcnt(8)
	s_waitcnt lgkmcnt(0)
	s_barrier
	s_setprio 1
	s_waitcnt lgkmcnt(0)
	v_mfma_f32_16x16x32_bf16 v[124:127], v[146:149], v[190:193], v[124:127]
	v_mfma_f32_16x16x32_bf16 v[124:127], v[150:153], v[194:197], v[124:127]
	v_mfma_f32_16x16x32_bf16 v[120:123], v[170:173], v[194:197], v[120:123]
	v_mfma_f32_16x16x32_bf16 v[120:123], v[162:165], v[190:193], v[120:123]
	v_mfma_f32_16x16x32_bf16 v[104:107], v[162:165], v[198:201], v[104:107]
	v_mfma_f32_16x16x32_bf16 v[104:107], v[170:173], v[202:205], v[104:107]
	v_mfma_f32_16x16x32_bf16 v[108:111], v[150:153], v[202:205], v[108:111]
	v_mfma_f32_16x16x32_bf16 v[108:111], v[146:149], v[198:201], v[108:111]
	v_mfma_f32_16x16x32_bf16 v[92:95], v[146:149], v[206:209], v[92:95]
	v_mfma_f32_16x16x32_bf16 v[92:95], v[150:153], v[210:213], v[92:95]
	v_mfma_f32_16x16x32_bf16 v[88:91], v[170:173], v[210:213], v[88:91]
	v_mfma_f32_16x16x32_bf16 v[88:91], v[162:165], v[206:209], v[88:91]
	v_mfma_f32_16x16x32_bf16 v[72:75], v[162:165], v[214:217], v[72:75]
	v_mfma_f32_16x16x32_bf16 v[72:75], v[170:173], v[218:221], v[72:75]
	v_mfma_f32_16x16x32_bf16 v[76:79], v[150:153], v[218:221], v[76:79]
	v_mfma_f32_16x16x32_bf16 v[76:79], v[146:149], v[214:217], v[76:79]
	s_setprio 0
	s_setprio 1
	v_mfma_f32_16x16x32_bf16 v[116:119], v[174:177], v[190:193], v[116:119]
	v_mfma_f32_16x16x32_bf16 v[116:119], v[178:181], v[194:197], v[116:119]
	v_mfma_f32_16x16x32_bf16 v[112:115], v[186:189], v[194:197], v[112:115]
	v_mfma_f32_16x16x32_bf16 v[112:115], v[182:185], v[190:193], v[112:115]
	v_mfma_f32_16x16x32_bf16 v[96:99], v[182:185], v[198:201], v[96:99]
	v_mfma_f32_16x16x32_bf16 v[96:99], v[186:189], v[202:205], v[96:99]
	v_mfma_f32_16x16x32_bf16 v[100:103], v[178:181], v[202:205], v[100:103]
	v_mfma_f32_16x16x32_bf16 v[100:103], v[174:177], v[198:201], v[100:103]
	v_mfma_f32_16x16x32_bf16 v[84:87], v[174:177], v[206:209], v[84:87]
	v_mfma_f32_16x16x32_bf16 v[84:87], v[178:181], v[210:213], v[84:87]
	v_mfma_f32_16x16x32_bf16 v[80:83], v[186:189], v[210:213], v[80:83]
	v_mfma_f32_16x16x32_bf16 v[80:83], v[182:185], v[206:209], v[80:83]
	v_mfma_f32_16x16x32_bf16 v[64:67], v[182:185], v[214:217], v[64:67]
	v_mfma_f32_16x16x32_bf16 v[64:67], v[186:189], v[218:221], v[64:67]
	v_mfma_f32_16x16x32_bf16 v[68:71], v[178:181], v[218:221], v[68:71]
	v_mfma_f32_16x16x32_bf16 v[68:71], v[174:177], v[214:217], v[68:71]
	s_setprio 0
	s_barrier
	s_add_i32 s34, s56, s12
	s_add_u32 s98, s50, 0x80
	s_addc_u32 s99, s51, 0
	s_mov_b32 m0, s34
	ds_read_b128 v[190:193], v161 offset:16384
	ds_read_b128 v[194:197], v161 offset:17408
	ds_read_b128 v[198:201], v161 offset:18432
	ds_read_b128 v[202:205], v161 offset:19456
	ds_read_b128 v[206:209], v161 offset:20480
	ds_read_b128 v[210:213], v161 offset:21504
	ds_read_b128 v[214:217], v161 offset:22528
	ds_read_b128 v[218:221], v161 offset:23552
	global_load_lds_dwordx4 v130, s[50:51]
	s_add_i32 m0, s34, 0x2000
	s_add_u32 s34, s50, 0x20000
	s_addc_u32 s35, s51, 0
	s_add_i32 s46, s57, s12
	global_load_lds_dwordx4 v134, s[50:51]
	s_mov_b32 m0, s46
	s_nop 0
	global_load_lds_dwordx4 v130, s[34:35]
	s_add_i32 m0, s46, 0x2000
	s_nop 0
	global_load_lds_dwordx4 v134, s[34:35]
	s_add_u32 s100, s52, 0x80
	s_addc_u32 s101, s53, 0
	s_mov_b32 m0, s13
	s_nop 0
	global_load_lds_dwordx4 v128, s[52:53]
	s_mov_b32 m0, s33
	s_nop 0
	global_load_lds_dwordx4 v132, s[52:53]
	s_waitcnt vmcnt(8)
	s_waitcnt lgkmcnt(0)
	s_barrier
	s_setprio 1
	s_waitcnt lgkmcnt(0)
	v_mfma_f32_16x16x32_bf16 v[60:63], v[146:149], v[190:193], v[60:63]
	v_mfma_f32_16x16x32_bf16 v[60:63], v[150:153], v[194:197], v[60:63]
	v_mfma_f32_16x16x32_bf16 v[56:59], v[170:173], v[194:197], v[56:59]
	v_mfma_f32_16x16x32_bf16 v[56:59], v[162:165], v[190:193], v[56:59]
	v_mfma_f32_16x16x32_bf16 v[40:43], v[162:165], v[198:201], v[40:43]
	v_mfma_f32_16x16x32_bf16 v[40:43], v[170:173], v[202:205], v[40:43]
	v_mfma_f32_16x16x32_bf16 v[44:47], v[150:153], v[202:205], v[44:47]
	v_mfma_f32_16x16x32_bf16 v[44:47], v[146:149], v[198:201], v[44:47]
	v_mfma_f32_16x16x32_bf16 v[28:31], v[146:149], v[206:209], v[28:31]
	v_mfma_f32_16x16x32_bf16 v[28:31], v[150:153], v[210:213], v[28:31]
	v_mfma_f32_16x16x32_bf16 v[24:27], v[170:173], v[210:213], v[24:27]
	v_mfma_f32_16x16x32_bf16 v[24:27], v[162:165], v[206:209], v[24:27]
	v_mfma_f32_16x16x32_bf16 v[8:11], v[162:165], v[214:217], v[8:11]
	v_mfma_f32_16x16x32_bf16 v[8:11], v[170:173], v[218:221], v[8:11]
	v_mfma_f32_16x16x32_bf16 v[12:15], v[150:153], v[218:221], v[12:15]
	v_mfma_f32_16x16x32_bf16 v[12:15], v[146:149], v[214:217], v[12:15]
	s_setprio 0
	s_setprio 1
	v_mfma_f32_16x16x32_bf16 v[52:55], v[174:177], v[190:193], v[52:55]
	v_mfma_f32_16x16x32_bf16 v[52:55], v[178:181], v[194:197], v[52:55]
	v_mfma_f32_16x16x32_bf16 v[48:51], v[186:189], v[194:197], v[48:51]
	v_mfma_f32_16x16x32_bf16 v[48:51], v[182:185], v[190:193], v[48:51]
	v_mfma_f32_16x16x32_bf16 v[32:35], v[182:185], v[198:201], v[32:35]
	v_mfma_f32_16x16x32_bf16 v[32:35], v[186:189], v[202:205], v[32:35]
	v_mfma_f32_16x16x32_bf16 v[36:39], v[178:181], v[202:205], v[36:39]
	v_mfma_f32_16x16x32_bf16 v[36:39], v[174:177], v[198:201], v[36:39]
	v_mfma_f32_16x16x32_bf16 v[20:23], v[174:177], v[206:209], v[20:23]
	v_mfma_f32_16x16x32_bf16 v[20:23], v[178:181], v[210:213], v[20:23]
	v_mfma_f32_16x16x32_bf16 v[16:19], v[186:189], v[210:213], v[16:19]
	v_mfma_f32_16x16x32_bf16 v[16:19], v[182:185], v[206:209], v[16:19]
	v_mfma_f32_16x16x32_bf16 v[0:3], v[182:185], v[214:217], v[0:3]
	v_mfma_f32_16x16x32_bf16 v[0:3], v[186:189], v[218:221], v[0:3]
	v_mfma_f32_16x16x32_bf16 v[4:7], v[178:181], v[218:221], v[4:7]
	v_mfma_f32_16x16x32_bf16 v[4:7], v[174:177], v[214:217], v[4:7]
	s_setprio 0
	s_barrier
; #define PG8_STAGE(bufoff, gbase, voff) do { _Pragma("unroll") for (int _i = 0; _i < 2; ++_i) \
;         __builtin_amdgcn_global_load_lds((const unsigned*)((const char*)(gbase) + (voff)[_i]), (LAS unsigned*)(lds + (bufoff) + ldsw + _i * 8192), 16, 0, 0); } while (0)
; #define PG8_LDA(dst, b, h) do { _Pragma("unroll") for (int m = 0; m < 4; ++m) _Pragma("unroll") for (int k = 0; k < 2; ++k) dst[m][k] = *(const LAS bf16x8*)(lds + PG8_SA(b, h) + aoff + m * 2048 + k * 1024); } while (0)
; #define PG8_LDB(dst, b, h) do { _Pragma("unroll") for (int n = 0; n < 2; ++n) _Pragma("unroll") for (int k = 0; k < 2; ++k) dst[n][k] = *(const LAS bf16x8*)(lds + PG8_SB(b, h) + boff + n * 2048 + k * 1024); } while (0)
; #define PG8_MMA(ai, bj, At, Bt) do { __builtin_amdgcn_s_setprio(1); _Pragma("unroll") for (int m = 0; m < 4; ++m) _Pragma("unroll") for (int n = 0; n < 2; ++n) _Pragma("unroll") for (int k = 0; k < 2; ++k) \
;         acc[ai][bj][m][n] = __builtin_amdgcn_mfma_f32_16x16x32_bf16(Bt[n][k], At[m][k], acc[ai][bj][m][n], 0, 0, 0); __builtin_amdgcn_s_setprio(0); } while (0)
; #define PG8_WAIT_V(n) asm volatile("s_waitcnt vmcnt(" #n ")" ::: "memory")
; #define PG8_WAIT_L(n) asm volatile("s_waitcnt lgkmcnt(" #n ")" ::: "memory")
; #define PG8_BAR __builtin_amdgcn_s_barrier()
; #define PG8_SCHED __builtin_amdgcn_sched_barrier(0)
; DI void gemm_phase(LAS unsigned char* lds, const Gemm g, const StaticOrder& S, const Epi& E) {
;     ...
;             PG8_LDB(B0, 1, 0); PG8_LDB(B1, 1, 1); PG8_SCHED; PG8_LDA(At, 1, 0); PG8_STAGE(PG8_SA(0, 1), a2 + hsA, voffA);
;             PG8_WAIT_V(8); PG8_WAIT_L(0); PG8_BAR; PG8_MMA(0, 0, At, B0); PG8_MMA(0, 1, At, B1); PG8_BAR; PG8_SCHED;
;             PG8_LDA(At, 1, 1); PG8_STAGE(PG8_SB(1, 0), b3, voffB); PG8_STAGE(PG8_SB(1, 1), b3 + hsB, voffB); PG8_STAGE(PG8_SA(1, 0), a3, voffA);
;             PG8_WAIT_V(8); PG8_WAIT_L(0); PG8_BAR; PG8_MMA(1, 0, At, B0); PG8_MMA(1, 1, At, B1); PG8_BAR; PG8_SCHED;
;         }
;         if (wr == 0) PG8_BAR;
	s_add_i32 s46, 0, 0x18000
	v_add_u32_e32 v136, s46, v157
	s_add_i32 s47, 0, 0x1c000
	ds_read_b128 v[146:149], v136
	ds_read_b128 v[150:153], v136 offset:1024
	ds_read_b128 v[162:165], v136 offset:2048
	ds_read_b128 v[170:173], v136 offset:3072
	v_add_u32_e32 v136, s47, v157
	ds_read_b128 v[174:177], v136
	ds_read_b128 v[178:181], v136 offset:1024
	ds_read_b128 v[182:185], v136 offset:2048
	ds_read_b128 v[186:189], v136 offset:3072
	s_add_u32 s34, s52, 0xb0000
	s_addc_u32 s35, s53, 0
	s_mov_b32 m0, s40
	ds_read_b128 v[190:193], v161 offset:32768
	ds_read_b128 v[194:197], v161 offset:33792
	ds_read_b128 v[198:201], v161 offset:34816
	ds_read_b128 v[202:205], v161 offset:35840
	ds_read_b128 v[206:209], v161 offset:36864
	ds_read_b128 v[210:213], v161 offset:37888
	ds_read_b128 v[214:217], v161 offset:38912
	ds_read_b128 v[218:221], v161 offset:39936
	global_load_lds_dwordx4 v128, s[34:35]
	s_mov_b32 m0, s41
	s_nop 0
	global_load_lds_dwordx4 v132, s[34:35]
	s_waitcnt vmcnt(8)
	s_waitcnt lgkmcnt(0)
	s_barrier
	s_setprio 1
	s_waitcnt lgkmcnt(0)
	v_mfma_f32_16x16x32_bf16 v[124:127], v[146:149], v[190:193], v[124:127]
	v_mfma_f32_16x16x32_bf16 v[124:127], v[150:153], v[194:197], v[124:127]
	v_mfma_f32_16x16x32_bf16 v[120:123], v[170:173], v[194:197], v[120:123]
	v_mfma_f32_16x16x32_bf16 v[120:123], v[162:165], v[190:193], v[120:123]
	v_mfma_f32_16x16x32_bf16 v[104:107], v[162:165], v[198:201], v[104:107]
	v_mfma_f32_16x16x32_bf16 v[104:107], v[170:173], v[202:205], v[104:107]
	v_mfma_f32_16x16x32_bf16 v[108:111], v[150:153], v[202:205], v[108:111]
	v_mfma_f32_16x16x32_bf16 v[108:111], v[146:149], v[198:201], v[108:111]
	v_mfma_f32_16x16x32_bf16 v[92:95], v[146:149], v[206:209], v[92:95]
	v_mfma_f32_16x16x32_bf16 v[92:95], v[150:153], v[210:213], v[92:95]
	v_mfma_f32_16x16x32_bf16 v[88:91], v[170:173], v[210:213], v[88:91]
	v_mfma_f32_16x16x32_bf16 v[88:91], v[162:165], v[206:209], v[88:91]
	v_mfma_f32_16x16x32_bf16 v[72:75], v[162:165], v[214:217], v[72:75]
	v_mfma_f32_16x16x32_bf16 v[72:75], v[170:173], v[218:221], v[72:75]
	v_mfma_f32_16x16x32_bf16 v[76:79], v[150:153], v[218:221], v[76:79]
	v_mfma_f32_16x16x32_bf16 v[76:79], v[146:149], v[214:217], v[76:79]
	s_setprio 0
	s_setprio 1
	v_mfma_f32_16x16x32_bf16 v[116:119], v[174:177], v[190:193], v[116:119]
	v_mfma_f32_16x16x32_bf16 v[116:119], v[178:181], v[194:197], v[116:119]
	v_mfma_f32_16x16x32_bf16 v[112:115], v[186:189], v[194:197], v[112:115]
	v_mfma_f32_16x16x32_bf16 v[112:115], v[182:185], v[190:193], v[112:115]
	v_mfma_f32_16x16x32_bf16 v[96:99], v[182:185], v[198:201], v[96:99]
	v_mfma_f32_16x16x32_bf16 v[96:99], v[186:189], v[202:205], v[96:99]
	v_mfma_f32_16x16x32_bf16 v[100:103], v[178:181], v[202:205], v[100:103]
	v_mfma_f32_16x16x32_bf16 v[100:103], v[174:177], v[198:201], v[100:103]
	v_mfma_f32_16x16x32_bf16 v[84:87], v[174:177], v[206:209], v[84:87]
	v_mfma_f32_16x16x32_bf16 v[84:87], v[178:181], v[210:213], v[84:87]
	v_mfma_f32_16x16x32_bf16 v[80:83], v[186:189], v[210:213], v[80:83]
	v_mfma_f32_16x16x32_bf16 v[80:83], v[182:185], v[206:209], v[80:83]
	v_mfma_f32_16x16x32_bf16 v[64:67], v[182:185], v[214:217], v[64:67]
	v_mfma_f32_16x16x32_bf16 v[64:67], v[186:189], v[218:221], v[64:67]
	v_mfma_f32_16x16x32_bf16 v[68:71], v[178:181], v[218:221], v[68:71]
	v_mfma_f32_16x16x32_bf16 v[68:71], v[174:177], v[214:217], v[68:71]
	s_setprio 0
	s_barrier
	s_add_i32 s34, s46, s12
	s_mov_b32 m0, s34
	ds_read_b128 v[190:193], v161 offset:49152
	ds_read_b128 v[194:197], v161 offset:50176
	ds_read_b128 v[198:201], v161 offset:51200
	ds_read_b128 v[202:205], v161 offset:52224
	ds_read_b128 v[206:209], v161 offset:53248
	ds_read_b128 v[210:213], v161 offset:54272
	ds_read_b128 v[214:217], v161 offset:55296
	ds_read_b128 v[218:221], v161 offset:56320
	global_load_lds_dwordx4 v130, s[98:99]
	s_add_i32 m0, s34, 0x2000
	s_add_u32 s34, s50, 0x20080
	s_addc_u32 s35, s51, 0
	s_add_i32 s46, s47, s12
	global_load_lds_dwordx4 v134, s[98:99]
	s_mov_b32 m0, s46
	s_nop 0
	global_load_lds_dwordx4 v130, s[34:35]
	s_add_i32 m0, s46, 0x2000
	s_nop 0
	global_load_lds_dwordx4 v134, s[34:35]
	s_mov_b32 m0, s48
	s_nop 0
	global_load_lds_dwordx4 v128, s[100:101]
	s_mov_b32 m0, s49
	s_nop 0
	global_load_lds_dwordx4 v132, s[100:101]
	s_waitcnt vmcnt(8)
	s_waitcnt lgkmcnt(0)
	s_barrier
	s_setprio 1
	s_waitcnt lgkmcnt(0)
	v_mfma_f32_16x16x32_bf16 v[60:63], v[146:149], v[190:193], v[60:63]
	v_mfma_f32_16x16x32_bf16 v[60:63], v[150:153], v[194:197], v[60:63]
	v_mfma_f32_16x16x32_bf16 v[56:59], v[170:173], v[194:197], v[56:59]
	v_mfma_f32_16x16x32_bf16 v[56:59], v[162:165], v[190:193], v[56:59]
	v_mfma_f32_16x16x32_bf16 v[40:43], v[162:165], v[198:201], v[40:43]
	v_mfma_f32_16x16x32_bf16 v[40:43], v[170:173], v[202:205], v[40:43]
	v_mfma_f32_16x16x32_bf16 v[44:47], v[150:153], v[202:205], v[44:47]
	v_mfma_f32_16x16x32_bf16 v[44:47], v[146:149], v[198:201], v[44:47]
	v_mfma_f32_16x16x32_bf16 v[28:31], v[146:149], v[206:209], v[28:31]
	v_mfma_f32_16x16x32_bf16 v[28:31], v[150:153], v[210:213], v[28:31]
	v_mfma_f32_16x16x32_bf16 v[24:27], v[170:173], v[210:213], v[24:27]
	v_mfma_f32_16x16x32_bf16 v[24:27], v[162:165], v[206:209], v[24:27]
	v_mfma_f32_16x16x32_bf16 v[8:11], v[162:165], v[214:217], v[8:11]
	v_mfma_f32_16x16x32_bf16 v[8:11], v[170:173], v[218:221], v[8:11]
	v_mfma_f32_16x16x32_bf16 v[12:15], v[150:153], v[218:221], v[12:15]
	v_mfma_f32_16x16x32_bf16 v[12:15], v[146:149], v[214:217], v[12:15]
	s_setprio 0
	s_setprio 1
	v_mfma_f32_16x16x32_bf16 v[52:55], v[174:177], v[190:193], v[52:55]
	v_mfma_f32_16x16x32_bf16 v[52:55], v[178:181], v[194:197], v[52:55]
	v_mfma_f32_16x16x32_bf16 v[48:51], v[186:189], v[194:197], v[48:51]
	v_mfma_f32_16x16x32_bf16 v[48:51], v[182:185], v[190:193], v[48:51]
	v_mfma_f32_16x16x32_bf16 v[32:35], v[182:185], v[198:201], v[32:35]
	v_mfma_f32_16x16x32_bf16 v[32:35], v[186:189], v[202:205], v[32:35]
	v_mfma_f32_16x16x32_bf16 v[36:39], v[178:181], v[202:205], v[36:39]
	v_mfma_f32_16x16x32_bf16 v[36:39], v[174:177], v[198:201], v[36:39]
	v_mfma_f32_16x16x32_bf16 v[20:23], v[174:177], v[206:209], v[20:23]
	v_mfma_f32_16x16x32_bf16 v[20:23], v[178:181], v[210:213], v[20:23]
	v_mfma_f32_16x16x32_bf16 v[16:19], v[186:189], v[210:213], v[16:19]
	v_mfma_f32_16x16x32_bf16 v[16:19], v[182:185], v[206:209], v[16:19]
	v_mfma_f32_16x16x32_bf16 v[0:3], v[182:185], v[214:217], v[0:3]
	v_mfma_f32_16x16x32_bf16 v[0:3], v[186:189], v[218:221], v[0:3]
	v_mfma_f32_16x16x32_bf16 v[4:7], v[178:181], v[218:221], v[4:7]
	v_mfma_f32_16x16x32_bf16 v[4:7], v[174:177], v[214:217], v[4:7]
	s_setprio 0
	s_barrier
	s_add_i32 s70, s70, 2
	s_add_u32 s68, s68, 0x100
	s_addc_u32 s69, s69, 0
	s_cmp_gt_u32 s70, 5
	s_mov_b64 s[34:35], s[4:5]
	s_cbranch_scc0 .LBB0_343
	s_and_b64 vcc, exec, s[22:23]
	s_cbranch_vccz .LBB0_346
	s_barrier

; #define PG8_STAGE(bufoff, gbase, voff) do { _Pragma("unroll") for (int _i = 0; _i < 2; ++_i) \
;         __builtin_amdgcn_global_load_lds((const unsigned*)((const char*)(gbase) + (voff)[_i]), (LAS unsigned*)(lds + (bufoff) + ldsw + _i * 8192), 16, 0, 0); } while (0)
; #define PG8_LDA(dst, b, h) do { _Pragma("unroll") for (int m = 0; m < 4; ++m) _Pragma("unroll") for (int k = 0; k < 2; ++k) dst[m][k] = *(const LAS bf16x8*)(lds + PG8_SA(b, h) + aoff + m * 2048 + k * 1024); } while (0)
; #define PG8_LDB(dst, b, h) do { _Pragma("unroll") for (int n = 0; n < 2; ++n) _Pragma("unroll") for (int k = 0; k < 2; ++k) dst[n][k] = *(const LAS bf16x8*)(lds + PG8_SB(b, h) + boff + n * 2048 + k * 1024); } while (0)
; #define PG8_MMA(ai, bj, At, Bt) do { __builtin_amdgcn_s_setprio(1); _Pragma("unroll") for (int m = 0; m < 4; ++m) _Pragma("unroll") for (int n = 0; n < 2; ++n) _Pragma("unroll") for (int k = 0; k < 2; ++k) \
;         acc[ai][bj][m][n] = __builtin_amdgcn_mfma_f32_16x16x32_bf16(Bt[n][k], At[m][k], acc[ai][bj][m][n], 0, 0, 0); __builtin_amdgcn_s_setprio(0); } while (0)
; #define PG8_WAIT_V(n) asm volatile("s_waitcnt vmcnt(" #n ")" ::: "memory")
; #define PG8_WAIT_L(n) asm volatile("s_waitcnt lgkmcnt(" #n ")" ::: "memory")
; #define PG8_BAR __builtin_amdgcn_s_barrier()
; #define PG8_SCHED __builtin_amdgcn_sched_barrier(0)
; DI void gemm_phase(LAS unsigned char* lds, const Gemm g, const StaticOrder& S, const Epi& E) {
;     ...
;         for (int t = 0; t < nt; t += 2) {
;             const bool last = (t == nt - 2);
;             const char* a1 = cA + (size_t)(t + 1) * kstep;
;             const char* a2 = last ? nA : cA + (size_t)(t + 2) * kstep; const char* b2 = last ? nB : cB + (size_t)(t + 2) * kstep;
;             const char* a3 = a2 + kstep; const char* b3 = b2 + kstep;
;             PG8_LDB(B0, 0, 0); PG8_LDB(B1, 0, 1); PG8_SCHED; PG8_LDA(At, 0, 0); PG8_STAGE(PG8_SA(1, 1), a1 + hsA, voffA);
;             PG8_WAIT_V(8); PG8_WAIT_L(0); PG8_BAR; PG8_MMA(0, 0, At, B0); PG8_MMA(0, 1, At, B1); PG8_BAR; PG8_SCHED;
;             PG8_LDA(At, 0, 1); PG8_STAGE(PG8_SB(0, 0), b2, voffB); PG8_STAGE(PG8_SB(0, 1), b2 + hsB, voffB); PG8_STAGE(PG8_SA(0, 0), a2, voffA);
.LBB0_403:
	s_add_u32 s47, s30, s46
	s_addc_u32 s66, s31, 0
	s_add_u32 s54, s47, 0x100
	s_addc_u32 s55, s66, 0
	s_and_b64 s[52:53], s[34:35], exec
	s_cselect_b32 s55, s23, s55
	s_cselect_b32 s54, s22, s54
	s_add_u32 s46, s28, s46
	s_addc_u32 s52, s29, 0
	s_add_u32 s46, s46, 0x100
	s_addc_u32 s52, s52, 0
	s_and_b64 s[34:35], s[34:35], exec
	s_cselect_b32 s57, s21, s52
	s_cselect_b32 s56, s27, s46
	s_add_u32 s68, s47, 0xb0080
	ds_read_b128 v[140:143], v153
	ds_read_b128 v[144:147], v153 offset:1024
	ds_read_b128 v[156:159], v153 offset:2048
	ds_read_b128 v[160:163], v153 offset:3072
	ds_read_b128 v[170:173], v154
	ds_read_b128 v[174:177], v154 offset:1024
	ds_read_b128 v[178:181], v154 offset:2048
	ds_read_b128 v[182:185], v154 offset:3072
	s_addc_u32 s69, s66, 0
	s_add_i32 s79, s70, s33
	s_add_i32 m0, s40, 0xc000
	s_add_i32 s82, s40, 0xe000
	s_add_i32 s76, s79, 0x2000
	s_add_u32 s66, s56, 0x10000
	s_addc_u32 s67, s57, 0
	s_add_i32 s78, s71, s33
	s_add_i32 s77, s78, 0x2000
	s_add_i32 s75, 0, 0x18000
	s_add_i32 s74, 0, 0x1c000
	s_add_u32 s52, s54, 0xb0000
	s_addc_u32 s53, s55, 0
	s_add_i32 s47, s75, s33
	s_add_i32 s46, s47, 0x2000
	s_add_u32 s34, s56, 0x10080
	s_addc_u32 s35, s57, 0
	s_add_i32 s81, s74, s33
	s_add_i32 s80, s81, 0x2000
	ds_read_b128 v[186:189], v155
	ds_read_b128 v[190:193], v155 offset:1024
	ds_read_b128 v[194:197], v155 offset:2048
	ds_read_b128 v[198:201], v155 offset:3072
	ds_read_b128 v[202:205], v155 offset:4096
	ds_read_b128 v[206:209], v155 offset:5120
	ds_read_b128 v[210:213], v155 offset:6144
	ds_read_b128 v[214:217], v155 offset:7168
	global_load_lds_dwordx4 v128, s[68:69]
	s_mov_b32 m0, s82
	s_nop 0
	global_load_lds_dwordx4 v132, s[68:69]
	s_waitcnt vmcnt(8)
	s_waitcnt lgkmcnt(0)
	s_barrier
	s_setprio 1
	s_waitcnt lgkmcnt(0)
	v_mfma_f32_16x16x32_bf16 v[124:127], v[140:143], v[186:189], v[124:127]
	v_mfma_f32_16x16x32_bf16 v[124:127], v[144:147], v[190:193], v[124:127]
	v_mfma_f32_16x16x32_bf16 v[120:123], v[160:163], v[190:193], v[120:123]
	v_mfma_f32_16x16x32_bf16 v[120:123], v[156:159], v[186:189], v[120:123]
	v_mfma_f32_16x16x32_bf16 v[104:107], v[156:159], v[194:197], v[104:107]
	v_mfma_f32_16x16x32_bf16 v[104:107], v[160:163], v[198:201], v[104:107]
	v_mfma_f32_16x16x32_bf16 v[108:111], v[144:147], v[198:201], v[108:111]
	v_mfma_f32_16x16x32_bf16 v[108:111], v[140:143], v[194:197], v[108:111]
	v_mfma_f32_16x16x32_bf16 v[92:95], v[140:143], v[202:205], v[92:95]
	v_mfma_f32_16x16x32_bf16 v[92:95], v[144:147], v[206:209], v[92:95]
	v_mfma_f32_16x16x32_bf16 v[88:91], v[160:163], v[206:209], v[88:91]
	v_mfma_f32_16x16x32_bf16 v[88:91], v[156:159], v[202:205], v[88:91]
	v_mfma_f32_16x16x32_bf16 v[72:75], v[156:159], v[210:213], v[72:75]
	v_mfma_f32_16x16x32_bf16 v[72:75], v[160:163], v[214:217], v[72:75]
	v_mfma_f32_16x16x32_bf16 v[76:79], v[144:147], v[214:217], v[76:79]
	v_mfma_f32_16x16x32_bf16 v[76:79], v[140:143], v[210:213], v[76:79]
	s_setprio 0
	s_setprio 1
	v_mfma_f32_16x16x32_bf16 v[116:119], v[170:173], v[186:189], v[116:119]
	v_mfma_f32_16x16x32_bf16 v[116:119], v[174:177], v[190:193], v[116:119]
	v_mfma_f32_16x16x32_bf16 v[112:115], v[182:185], v[190:193], v[112:115]
	v_mfma_f32_16x16x32_bf16 v[112:115], v[178:181], v[186:189], v[112:115]
	v_mfma_f32_16x16x32_bf16 v[96:99], v[178:181], v[194:197], v[96:99]
	v_mfma_f32_16x16x32_bf16 v[96:99], v[182:185], v[198:201], v[96:99]
	v_mfma_f32_16x16x32_bf16 v[100:103], v[174:177], v[198:201], v[100:103]
	v_mfma_f32_16x16x32_bf16 v[100:103], v[170:173], v[194:197], v[100:103]
	v_mfma_f32_16x16x32_bf16 v[84:87], v[170:173], v[202:205], v[84:87]
	v_mfma_f32_16x16x32_bf16 v[84:87], v[174:177], v[206:209], v[84:87]
	v_mfma_f32_16x16x32_bf16 v[80:83], v[182:185], v[206:209], v[80:83]
	v_mfma_f32_16x16x32_bf16 v[80:83], v[178:181], v[202:205], v[80:83]
	v_mfma_f32_16x16x32_bf16 v[64:67], v[178:181], v[210:213], v[64:67]
	v_mfma_f32_16x16x32_bf16 v[64:67], v[182:185], v[214:217], v[64:67]
	v_mfma_f32_16x16x32_bf16 v[68:71], v[174:177], v[214:217], v[68:71]
	v_mfma_f32_16x16x32_bf16 v[68:71], v[170:173], v[210:213], v[68:71]
	s_setprio 0
	s_barrier
	s_mov_b32 m0, s79
	s_add_u32 s98, s56, 0x80
	s_addc_u32 s99, s57, 0
	ds_read_b128 v[186:189], v155 offset:16384
	ds_read_b128 v[190:193], v155 offset:17408
	ds_read_b128 v[194:197], v155 offset:18432
	ds_read_b128 v[198:201], v155 offset:19456
	ds_read_b128 v[202:205], v155 offset:20480
	ds_read_b128 v[206:209], v155 offset:21504
	ds_read_b128 v[210:213], v155 offset:22528
	ds_read_b128 v[214:217], v155 offset:23552
	global_load_lds_dwordx4 v130, s[56:57]
	s_mov_b32 m0, s76
	s_nop 0
	global_load_lds_dwordx4 v134, s[56:57]
	s_mov_b32 m0, s78
	s_nop 0
	global_load_lds_dwordx4 v130, s[66:67]
	s_mov_b32 m0, s77
	s_nop 0
	global_load_lds_dwordx4 v134, s[66:67]
	s_add_u32 s100, s54, 0x80
	s_addc_u32 s101, s55, 0
	s_mov_b32 m0, s40
	s_nop 0
	global_load_lds_dwordx4 v128, s[54:55]
	s_mov_b32 m0, s41
	s_nop 0
	global_load_lds_dwordx4 v132, s[54:55]
	s_waitcnt vmcnt(8)
	s_waitcnt lgkmcnt(0)
	s_barrier
; #define PG8_STAGE(bufoff, gbase, voff) do { _Pragma("unroll") for (int _i = 0; _i < 2; ++_i) \
;         __builtin_amdgcn_global_load_lds((const unsigned*)((const char*)(gbase) + (voff)[_i]), (LAS unsigned*)(lds + (bufoff) + ldsw + _i * 8192), 16, 0, 0); } while (0)
; #define PG8_LDA(dst, b, h) do { _Pragma("unroll") for (int m = 0; m < 4; ++m) _Pragma("unroll") for (int k = 0; k < 2; ++k) dst[m][k] = *(const LAS bf16x8*)(lds + PG8_SA(b, h) + aoff + m * 2048 + k * 1024); } while (0)
; #define PG8_LDB(dst, b, h) do { _Pragma("unroll") for (int n = 0; n < 2; ++n) _Pragma("unroll") for (int k = 0; k < 2; ++k) dst[n][k] = *(const LAS bf16x8*)(lds + PG8_SB(b, h) + boff + n * 2048 + k * 1024); } while (0)
; #define PG8_MMA(ai, bj, At, Bt) do { __builtin_amdgcn_s_setprio(1); _Pragma("unroll") for (int m = 0; m < 4; ++m) _Pragma("unroll") for (int n = 0; n < 2; ++n) _Pragma("unroll") for (int k = 0; k < 2; ++k) \
;         acc[ai][bj][m][n] = __builtin_amdgcn_mfma_f32_16x16x32_bf16(Bt[n][k], At[m][k], acc[ai][bj][m][n], 0, 0, 0); __builtin_amdgcn_s_setprio(0); } while (0)
; #define PG8_WAIT_V(n) asm volatile("s_waitcnt vmcnt(" #n ")" ::: "memory")
; #define PG8_WAIT_L(n) asm volatile("s_waitcnt lgkmcnt(" #n ")" ::: "memory")
; #define PG8_BAR __builtin_amdgcn_s_barrier()
; #define PG8_SCHED __builtin_amdgcn_sched_barrier(0)
; DI void gemm_phase(LAS unsigned char* lds, const Gemm g, const StaticOrder& S, const Epi& E) {
;     ...
;             PG8_WAIT_V(8); PG8_WAIT_L(0); PG8_BAR; PG8_MMA(1, 0, At, B0); PG8_MMA(1, 1, At, B1); PG8_BAR; PG8_SCHED;
;             PG8_LDB(B0, 1, 0); PG8_LDB(B1, 1, 1); PG8_SCHED; PG8_LDA(At, 1, 0); PG8_STAGE(PG8_SA(0, 1), a2 + hsA, voffA);
;             PG8_WAIT_V(8); PG8_WAIT_L(0); PG8_BAR; PG8_MMA(0, 0, At, B0); PG8_MMA(0, 1, At, B1); PG8_BAR; PG8_SCHED;
	s_setprio 1
	s_waitcnt lgkmcnt(0)
	v_mfma_f32_16x16x32_bf16 v[60:63], v[140:143], v[186:189], v[60:63]
	v_mfma_f32_16x16x32_bf16 v[60:63], v[144:147], v[190:193], v[60:63]
	v_mfma_f32_16x16x32_bf16 v[56:59], v[160:163], v[190:193], v[56:59]
	v_mfma_f32_16x16x32_bf16 v[56:59], v[156:159], v[186:189], v[56:59]
	v_mfma_f32_16x16x32_bf16 v[40:43], v[156:159], v[194:197], v[40:43]
	v_mfma_f32_16x16x32_bf16 v[40:43], v[160:163], v[198:201], v[40:43]
	v_mfma_f32_16x16x32_bf16 v[44:47], v[144:147], v[198:201], v[44:47]
	v_mfma_f32_16x16x32_bf16 v[44:47], v[140:143], v[194:197], v[44:47]
	v_mfma_f32_16x16x32_bf16 v[28:31], v[140:143], v[202:205], v[28:31]
	v_mfma_f32_16x16x32_bf16 v[28:31], v[144:147], v[206:209], v[28:31]
	v_mfma_f32_16x16x32_bf16 v[24:27], v[160:163], v[206:209], v[24:27]
	v_mfma_f32_16x16x32_bf16 v[24:27], v[156:159], v[202:205], v[24:27]
	v_mfma_f32_16x16x32_bf16 v[8:11], v[156:159], v[210:213], v[8:11]
	v_mfma_f32_16x16x32_bf16 v[8:11], v[160:163], v[214:217], v[8:11]
	v_mfma_f32_16x16x32_bf16 v[12:15], v[144:147], v[214:217], v[12:15]
	v_mfma_f32_16x16x32_bf16 v[12:15], v[140:143], v[210:213], v[12:15]
	s_setprio 0
	s_setprio 1
	v_mfma_f32_16x16x32_bf16 v[52:55], v[170:173], v[186:189], v[52:55]
	v_mfma_f32_16x16x32_bf16 v[52:55], v[174:177], v[190:193], v[52:55]
	v_mfma_f32_16x16x32_bf16 v[48:51], v[182:185], v[190:193], v[48:51]
	v_mfma_f32_16x16x32_bf16 v[48:51], v[178:181], v[186:189], v[48:51]
	v_mfma_f32_16x16x32_bf16 v[32:35], v[178:181], v[194:197], v[32:35]
	v_mfma_f32_16x16x32_bf16 v[32:35], v[182:185], v[198:201], v[32:35]
	v_mfma_f32_16x16x32_bf16 v[36:39], v[174:177], v[198:201], v[36:39]
	v_mfma_f32_16x16x32_bf16 v[36:39], v[170:173], v[194:197], v[36:39]
	v_mfma_f32_16x16x32_bf16 v[20:23], v[170:173], v[202:205], v[20:23]
	v_mfma_f32_16x16x32_bf16 v[20:23], v[174:177], v[206:209], v[20:23]
	v_mfma_f32_16x16x32_bf16 v[16:19], v[182:185], v[206:209], v[16:19]
	v_mfma_f32_16x16x32_bf16 v[16:19], v[178:181], v[202:205], v[16:19]
	v_mfma_f32_16x16x32_bf16 v[0:3], v[178:181], v[210:213], v[0:3]
	v_mfma_f32_16x16x32_bf16 v[0:3], v[182:185], v[214:217], v[0:3]
	v_mfma_f32_16x16x32_bf16 v[4:7], v[174:177], v[214:217], v[4:7]
	v_mfma_f32_16x16x32_bf16 v[4:7], v[170:173], v[210:213], v[4:7]
	s_setprio 0
	s_barrier
	v_add_u32_e32 v160, s75, v151
	v_add_u32_e32 v166, s74, v151
	ds_read_b128 v[140:143], v160
	ds_read_b128 v[144:147], v160 offset:1024
	ds_read_b128 v[156:159], v160 offset:2048
	ds_read_b128 v[160:163], v160 offset:3072
	ds_read_b128 v[170:173], v166
	ds_read_b128 v[174:177], v166 offset:1024
	ds_read_b128 v[178:181], v166 offset:2048
	ds_read_b128 v[182:185], v166 offset:3072
	s_mov_b32 m0, s42
	ds_read_b128 v[186:189], v155 offset:32768
	ds_read_b128 v[190:193], v155 offset:33792
	ds_read_b128 v[194:197], v155 offset:34816
	ds_read_b128 v[198:201], v155 offset:35840
	ds_read_b128 v[202:205], v155 offset:36864
	ds_read_b128 v[206:209], v155 offset:37888
	ds_read_b128 v[210:213], v155 offset:38912
	ds_read_b128 v[214:217], v155 offset:39936
	global_load_lds_dwordx4 v128, s[52:53]
	s_mov_b32 m0, s43
	s_nop 0
	global_load_lds_dwordx4 v132, s[52:53]
	s_waitcnt vmcnt(8)
	s_waitcnt lgkmcnt(0)
	s_barrier
	s_setprio 1
	s_waitcnt lgkmcnt(0)
	v_mfma_f32_16x16x32_bf16 v[124:127], v[140:143], v[186:189], v[124:127]
	v_mfma_f32_16x16x32_bf16 v[124:127], v[144:147], v[190:193], v[124:127]
	v_mfma_f32_16x16x32_bf16 v[120:123], v[160:163], v[190:193], v[120:123]
	v_mfma_f32_16x16x32_bf16 v[120:123], v[156:159], v[186:189], v[120:123]
	v_mfma_f32_16x16x32_bf16 v[104:107], v[156:159], v[194:197], v[104:107]
	v_mfma_f32_16x16x32_bf16 v[104:107], v[160:163], v[198:201], v[104:107]
	v_mfma_f32_16x16x32_bf16 v[108:111], v[144:147], v[198:201], v[108:111]
	v_mfma_f32_16x16x32_bf16 v[108:111], v[140:143], v[194:197], v[108:111]
	v_mfma_f32_16x16x32_bf16 v[92:95], v[140:143], v[202:205], v[92:95]
	v_mfma_f32_16x16x32_bf16 v[92:95], v[144:147], v[206:209], v[92:95]
	v_mfma_f32_16x16x32_bf16 v[88:91], v[160:163], v[206:209], v[88:91]
	v_mfma_f32_16x16x32_bf16 v[88:91], v[156:159], v[202:205], v[88:91]
	v_mfma_f32_16x16x32_bf16 v[72:75], v[156:159], v[210:213], v[72:75]
	v_mfma_f32_16x16x32_bf16 v[72:75], v[160:163], v[214:217], v[72:75]
	v_mfma_f32_16x16x32_bf16 v[76:79], v[144:147], v[214:217], v[76:79]
	v_mfma_f32_16x16x32_bf16 v[76:79], v[140:143], v[210:213], v[76:79]
	s_setprio 0
	s_setprio 1
	v_mfma_f32_16x16x32_bf16 v[116:119], v[170:173], v[186:189], v[116:119]
	v_mfma_f32_16x16x32_bf16 v[116:119], v[174:177], v[190:193], v[116:119]
	v_mfma_f32_16x16x32_bf16 v[112:115], v[182:185], v[190:193], v[112:115]
	v_mfma_f32_16x16x32_bf16 v[112:115], v[178:181], v[186:189], v[112:115]
	v_mfma_f32_16x16x32_bf16 v[96:99], v[178:181], v[194:197], v[96:99]
	v_mfma_f32_16x16x32_bf16 v[96:99], v[182:185], v[198:201], v[96:99]
	v_mfma_f32_16x16x32_bf16 v[100:103], v[174:177], v[198:201], v[100:103]
	v_mfma_f32_16x16x32_bf16 v[100:103], v[170:173], v[194:197], v[100:103]
	v_mfma_f32_16x16x32_bf16 v[84:87], v[170:173], v[202:205], v[84:87]
	v_mfma_f32_16x16x32_bf16 v[84:87], v[174:177], v[206:209], v[84:87]
	v_mfma_f32_16x16x32_bf16 v[80:83], v[182:185], v[206:209], v[80:83]
	v_mfma_f32_16x16x32_bf16 v[80:83], v[178:181], v[202:205], v[80:83]
	v_mfma_f32_16x16x32_bf16 v[64:67], v[178:181], v[210:213], v[64:67]
	v_mfma_f32_16x16x32_bf16 v[64:67], v[182:185], v[214:217], v[64:67]
	v_mfma_f32_16x16x32_bf16 v[68:71], v[174:177], v[214:217], v[68:71]
	v_mfma_f32_16x16x32_bf16 v[68:71], v[170:173], v[210:213], v[68:71]
	s_setprio 0
	s_barrier
; #define PG8_STAGE(bufoff, gbase, voff) do { _Pragma("unroll") for (int _i = 0; _i < 2; ++_i) \
;         __builtin_amdgcn_global_load_lds((const unsigned*)((const char*)(gbase) + (voff)[_i]), (LAS unsigned*)(lds + (bufoff) + ldsw + _i * 8192), 16, 0, 0); } while (0)
; #define PG8_LDA(dst, b, h) do { _Pragma("unroll") for (int m = 0; m < 4; ++m) _Pragma("unroll") for (int k = 0; k < 2; ++k) dst[m][k] = *(const LAS bf16x8*)(lds + PG8_SA(b, h) + aoff + m * 2048 + k * 1024); } while (0)
; #define PG8_MMA(ai, bj, At, Bt) do { __builtin_amdgcn_s_setprio(1); _Pragma("unroll") for (int m = 0; m < 4; ++m) _Pragma("unroll") for (int n = 0; n < 2; ++n) _Pragma("unroll") for (int k = 0; k < 2; ++k) \
;         acc[ai][bj][m][n] = __builtin_amdgcn_mfma_f32_16x16x32_bf16(Bt[n][k], At[m][k], acc[ai][bj][m][n], 0, 0, 0); __builtin_amdgcn_s_setprio(0); } while (0)
; #define PG8_WAIT_V(n) asm volatile("s_waitcnt vmcnt(" #n ")" ::: "memory")
; #define PG8_WAIT_L(n) asm volatile("s_waitcnt lgkmcnt(" #n ")" ::: "memory")
; #define PG8_BAR __builtin_amdgcn_s_barrier()
; #define PG8_SCHED __builtin_amdgcn_sched_barrier(0)
; DI void gemm_phase(LAS unsigned char* lds, const Gemm g, const StaticOrder& S, const Epi& E) {
;     ...
;             PG8_LDA(At, 1, 1); PG8_STAGE(PG8_SB(1, 0), b3, voffB); PG8_STAGE(PG8_SB(1, 1), b3 + hsB, voffB); PG8_STAGE(PG8_SA(1, 0), a3, voffA);
;             PG8_WAIT_V(8); PG8_WAIT_L(0); PG8_BAR; PG8_MMA(1, 0, At, B0); PG8_MMA(1, 1, At, B1); PG8_BAR; PG8_SCHED;
;         }
;         if (wr == 0) PG8_BAR;
	s_mov_b32 m0, s47
	ds_read_b128 v[186:189], v155 offset:49152
	ds_read_b128 v[190:193], v155 offset:50176
	ds_read_b128 v[194:197], v155 offset:51200
	ds_read_b128 v[198:201], v155 offset:52224
	ds_read_b128 v[202:205], v155 offset:53248
	ds_read_b128 v[206:209], v155 offset:54272
	ds_read_b128 v[210:213], v155 offset:55296
	ds_read_b128 v[214:217], v155 offset:56320
	global_load_lds_dwordx4 v130, s[98:99]
	s_mov_b32 m0, s46
	s_nop 0
	global_load_lds_dwordx4 v134, s[98:99]
	s_mov_b32 m0, s81
	s_nop 0
	global_load_lds_dwordx4 v130, s[34:35]
	s_mov_b32 m0, s80
	s_nop 0
	global_load_lds_dwordx4 v134, s[34:35]
	s_mov_b32 m0, s58
	s_nop 0
	global_load_lds_dwordx4 v128, s[100:101]
	s_mov_b32 m0, s59
	s_nop 0
	global_load_lds_dwordx4 v132, s[100:101]
	s_waitcnt vmcnt(8)
	s_waitcnt lgkmcnt(0)
	s_barrier
	s_setprio 1
	s_waitcnt lgkmcnt(0)
	v_mfma_f32_16x16x32_bf16 v[60:63], v[140:143], v[186:189], v[60:63]
	v_mfma_f32_16x16x32_bf16 v[60:63], v[144:147], v[190:193], v[60:63]
	v_mfma_f32_16x16x32_bf16 v[56:59], v[160:163], v[190:193], v[56:59]
	v_mfma_f32_16x16x32_bf16 v[56:59], v[156:159], v[186:189], v[56:59]
	v_mfma_f32_16x16x32_bf16 v[40:43], v[156:159], v[194:197], v[40:43]
	v_mfma_f32_16x16x32_bf16 v[40:43], v[160:163], v[198:201], v[40:43]
	v_mfma_f32_16x16x32_bf16 v[44:47], v[144:147], v[198:201], v[44:47]
	v_mfma_f32_16x16x32_bf16 v[44:47], v[140:143], v[194:197], v[44:47]
	v_mfma_f32_16x16x32_bf16 v[28:31], v[140:143], v[202:205], v[28:31]
	v_mfma_f32_16x16x32_bf16 v[28:31], v[144:147], v[206:209], v[28:31]
	v_mfma_f32_16x16x32_bf16 v[24:27], v[160:163], v[206:209], v[24:27]
	v_mfma_f32_16x16x32_bf16 v[24:27], v[156:159], v[202:205], v[24:27]
	v_mfma_f32_16x16x32_bf16 v[8:11], v[156:159], v[210:213], v[8:11]
	v_mfma_f32_16x16x32_bf16 v[8:11], v[160:163], v[214:217], v[8:11]
	v_mfma_f32_16x16x32_bf16 v[12:15], v[144:147], v[214:217], v[12:15]
	v_mfma_f32_16x16x32_bf16 v[12:15], v[140:143], v[210:213], v[12:15]
	s_setprio 0
	s_setprio 1
	v_mfma_f32_16x16x32_bf16 v[52:55], v[170:173], v[186:189], v[52:55]
	v_mfma_f32_16x16x32_bf16 v[52:55], v[174:177], v[190:193], v[52:55]
	v_mfma_f32_16x16x32_bf16 v[48:51], v[182:185], v[190:193], v[48:51]
	v_mfma_f32_16x16x32_bf16 v[48:51], v[178:181], v[186:189], v[48:51]
	v_mfma_f32_16x16x32_bf16 v[32:35], v[178:181], v[194:197], v[32:35]
	v_mfma_f32_16x16x32_bf16 v[32:35], v[182:185], v[198:201], v[32:35]
	v_mfma_f32_16x16x32_bf16 v[36:39], v[174:177], v[198:201], v[36:39]
	v_mfma_f32_16x16x32_bf16 v[36:39], v[170:173], v[194:197], v[36:39]
	v_mfma_f32_16x16x32_bf16 v[20:23], v[170:173], v[202:205], v[20:23]
	v_mfma_f32_16x16x32_bf16 v[20:23], v[174:177], v[206:209], v[20:23]
	v_mfma_f32_16x16x32_bf16 v[16:19], v[182:185], v[206:209], v[16:19]
	v_mfma_f32_16x16x32_bf16 v[16:19], v[178:181], v[202:205], v[16:19]
	v_mfma_f32_16x16x32_bf16 v[0:3], v[178:181], v[210:213], v[0:3]
	v_mfma_f32_16x16x32_bf16 v[0:3], v[182:185], v[214:217], v[0:3]
	v_mfma_f32_16x16x32_bf16 v[4:7], v[174:177], v[214:217], v[4:7]
	v_mfma_f32_16x16x32_bf16 v[4:7], v[170:173], v[210:213], v[4:7]
	s_setprio 0
	s_barrier
	s_movk_i32 s46, 0x100
	s_andn2_b64 vcc, exec, s[6:7]
	s_mov_b64 s[34:35], -1
	s_mov_b64 s[6:7], 0
	s_cbranch_vccz .LBB0_403
	s_and_b64 vcc, exec, s[18:19]
	s_cbranch_vccz .LBB0_406
	s_barrier

; #define PG8_STAGE(bufoff, gbase, voff) do { _Pragma("unroll") for (int _i = 0; _i < 2; ++_i) \
;         __builtin_amdgcn_global_load_lds((const unsigned*)((const char*)(gbase) + (voff)[_i]), (LAS unsigned*)(lds + (bufoff) + ldsw + _i * 8192), 16, 0, 0); } while (0)
; #define PG8_LDA(dst, b, h) do { _Pragma("unroll") for (int m = 0; m < 4; ++m) _Pragma("unroll") for (int k = 0; k < 2; ++k) dst[m][k] = *(const LAS bf16x8*)(lds + PG8_SA(b, h) + aoff + m * 2048 + k * 1024); } while (0)
; #define PG8_LDB(dst, b, h) do { _Pragma("unroll") for (int n = 0; n < 2; ++n) _Pragma("unroll") for (int k = 0; k < 2; ++k) dst[n][k] = *(const LAS bf16x8*)(lds + PG8_SB(b, h) + boff + n * 2048 + k * 1024); } while (0)
; #define PG8_MMA(ai, bj, At, Bt) do { __builtin_amdgcn_s_setprio(1); _Pragma("unroll") for (int m = 0; m < 4; ++m) _Pragma("unroll") for (int n = 0; n < 2; ++n) _Pragma("unroll") for (int k = 0; k < 2; ++k) \
;         acc[ai][bj][m][n] = __builtin_amdgcn_mfma_f32_16x16x32_bf16(Bt[n][k], At[m][k], acc[ai][bj][m][n], 0, 0, 0); __builtin_amdgcn_s_setprio(0); } while (0)
; #define PG8_WAIT_V(n) asm volatile("s_waitcnt vmcnt(" #n ")" ::: "memory")
; #define PG8_WAIT_L(n) asm volatile("s_waitcnt lgkmcnt(" #n ")" ::: "memory")
; #define PG8_BAR __builtin_amdgcn_s_barrier()
; #define PG8_SCHED __builtin_amdgcn_sched_barrier(0)
; DI void gemm_phase(LAS unsigned char* lds, const Gemm g, const StaticOrder& S, const Epi& E) {
;     ...
;         for (int t = 0; t < nt; t += 2) {
;             const bool last = (t == nt - 2);
;             const char* a1 = cA + (size_t)(t + 1) * kstep;
;             const char* a2 = last ? nA : cA + (size_t)(t + 2) * kstep; const char* b2 = last ? nB : cB + (size_t)(t + 2) * kstep;
;             const char* a3 = a2 + kstep; const char* b3 = b2 + kstep;
;             PG8_LDB(B0, 0, 0); PG8_LDB(B1, 0, 1); PG8_SCHED; PG8_LDA(At, 0, 0); PG8_STAGE(PG8_SA(1, 1), a1 + hsA, voffA);
;             PG8_WAIT_V(8); PG8_WAIT_L(0); PG8_BAR; PG8_MMA(0, 0, At, B0); PG8_MMA(0, 1, At, B1); PG8_BAR; PG8_SCHED;
;             PG8_LDA(At, 0, 1); PG8_STAGE(PG8_SB(0, 0), b2, voffB); PG8_STAGE(PG8_SB(0, 1), b2 + hsB, voffB); PG8_STAGE(PG8_SA(0, 0), a2, voffA);
.LBB0_461:
	s_add_u32 s47, s30, s46
	s_addc_u32 s68, s31, 0
	s_add_u32 s56, s47, 0x100
	s_addc_u32 s57, s68, 0
	s_and_b64 s[54:55], s[34:35], exec
	s_cselect_b32 s57, s21, s57
	s_cselect_b32 s56, s76, s56
	s_add_u32 s46, s28, s46
	s_addc_u32 s54, s29, 0
	s_add_u32 s46, s46, 0x100
	s_addc_u32 s54, s54, 0
	s_and_b64 s[34:35], s[34:35], exec
	s_cselect_b32 s67, s23, s54
	s_cselect_b32 s66, s22, s46
	s_add_u32 s70, s47, 0x10080
	s_addc_u32 s71, s68, 0
	s_add_i32 s84, s58, s33
	ds_read_b128 v[140:143], v149
	ds_read_b128 v[152:155], v149 offset:1024
	ds_read_b128 v[156:159], v149 offset:2048
	ds_read_b128 v[160:163], v149 offset:3072
	ds_read_b128 v[170:173], v150
	ds_read_b128 v[174:177], v150 offset:1024
	ds_read_b128 v[178:181], v150 offset:2048
	ds_read_b128 v[182:185], v150 offset:3072
	s_add_i32 m0, s27, 0xc000
	s_add_i32 s85, s27, 0xe000
	s_add_i32 s81, s84, 0x2000
	s_add_u32 s68, s66, 0xb0000
	s_addc_u32 s69, s67, 0
	s_add_i32 s83, s59, s33
	s_add_i32 s82, s83, 0x2000
	s_add_i32 s80, 0, 0x18000
	s_add_i32 s79, 0, 0x1c000
	s_add_u32 s54, s56, 0x10000
	s_addc_u32 s55, s57, 0
	s_add_i32 s78, s80, s33
	s_add_i32 s47, s78, 0x2000
	s_add_u32 s34, s66, 0xb0080
	s_addc_u32 s35, s67, 0
	s_add_i32 s77, s79, s33
	s_add_i32 s46, s77, 0x2000
	ds_read_b128 v[186:189], v151
	ds_read_b128 v[190:193], v151 offset:1024
	ds_read_b128 v[194:197], v151 offset:2048
	ds_read_b128 v[198:201], v151 offset:3072
	ds_read_b128 v[202:205], v151 offset:4096
	ds_read_b128 v[206:209], v151 offset:5120
	ds_read_b128 v[210:213], v151 offset:6144
	ds_read_b128 v[214:217], v151 offset:7168
	global_load_lds_dwordx4 v128, s[70:71]
	s_mov_b32 m0, s85
	s_nop 0
	global_load_lds_dwordx4 v132, s[70:71]
	s_waitcnt vmcnt(8)
	s_waitcnt lgkmcnt(0)
	s_barrier
	s_setprio 1
	s_waitcnt lgkmcnt(0)
	v_mfma_f32_16x16x32_bf16 v[124:127], v[140:143], v[186:189], v[124:127]
	v_mfma_f32_16x16x32_bf16 v[124:127], v[152:155], v[190:193], v[124:127]
	v_mfma_f32_16x16x32_bf16 v[120:123], v[160:163], v[190:193], v[120:123]
	v_mfma_f32_16x16x32_bf16 v[120:123], v[156:159], v[186:189], v[120:123]
	v_mfma_f32_16x16x32_bf16 v[104:107], v[156:159], v[194:197], v[104:107]
	v_mfma_f32_16x16x32_bf16 v[104:107], v[160:163], v[198:201], v[104:107]
	v_mfma_f32_16x16x32_bf16 v[108:111], v[152:155], v[198:201], v[108:111]
	v_mfma_f32_16x16x32_bf16 v[108:111], v[140:143], v[194:197], v[108:111]
	v_mfma_f32_16x16x32_bf16 v[92:95], v[140:143], v[202:205], v[92:95]
	v_mfma_f32_16x16x32_bf16 v[92:95], v[152:155], v[206:209], v[92:95]
	v_mfma_f32_16x16x32_bf16 v[88:91], v[160:163], v[206:209], v[88:91]
	v_mfma_f32_16x16x32_bf16 v[88:91], v[156:159], v[202:205], v[88:91]
	v_mfma_f32_16x16x32_bf16 v[72:75], v[156:159], v[210:213], v[72:75]
	v_mfma_f32_16x16x32_bf16 v[72:75], v[160:163], v[214:217], v[72:75]
	v_mfma_f32_16x16x32_bf16 v[76:79], v[152:155], v[214:217], v[76:79]
	v_mfma_f32_16x16x32_bf16 v[76:79], v[140:143], v[210:213], v[76:79]
	s_setprio 0
	s_setprio 1
	v_mfma_f32_16x16x32_bf16 v[116:119], v[170:173], v[186:189], v[116:119]
	v_mfma_f32_16x16x32_bf16 v[116:119], v[174:177], v[190:193], v[116:119]
	v_mfma_f32_16x16x32_bf16 v[112:115], v[182:185], v[190:193], v[112:115]
	v_mfma_f32_16x16x32_bf16 v[112:115], v[178:181], v[186:189], v[112:115]
	v_mfma_f32_16x16x32_bf16 v[96:99], v[178:181], v[194:197], v[96:99]
	v_mfma_f32_16x16x32_bf16 v[96:99], v[182:185], v[198:201], v[96:99]
	v_mfma_f32_16x16x32_bf16 v[100:103], v[174:177], v[198:201], v[100:103]
	v_mfma_f32_16x16x32_bf16 v[100:103], v[170:173], v[194:197], v[100:103]
	v_mfma_f32_16x16x32_bf16 v[84:87], v[170:173], v[202:205], v[84:87]
	v_mfma_f32_16x16x32_bf16 v[84:87], v[174:177], v[206:209], v[84:87]
	v_mfma_f32_16x16x32_bf16 v[80:83], v[182:185], v[206:209], v[80:83]
	v_mfma_f32_16x16x32_bf16 v[80:83], v[178:181], v[202:205], v[80:83]
	v_mfma_f32_16x16x32_bf16 v[64:67], v[178:181], v[210:213], v[64:67]
	v_mfma_f32_16x16x32_bf16 v[64:67], v[182:185], v[214:217], v[64:67]
	v_mfma_f32_16x16x32_bf16 v[68:71], v[174:177], v[214:217], v[68:71]
	v_mfma_f32_16x16x32_bf16 v[68:71], v[170:173], v[210:213], v[68:71]
	s_setprio 0
	s_barrier
	s_mov_b32 m0, s84
	s_add_u32 s98, s66, 0x80
	s_addc_u32 s99, s67, 0
	ds_read_b128 v[186:189], v151 offset:16384
	ds_read_b128 v[190:193], v151 offset:17408
	ds_read_b128 v[194:197], v151 offset:18432
	ds_read_b128 v[198:201], v151 offset:19456
	ds_read_b128 v[202:205], v151 offset:20480
	ds_read_b128 v[206:209], v151 offset:21504
	ds_read_b128 v[210:213], v151 offset:22528
	ds_read_b128 v[214:217], v151 offset:23552
	global_load_lds_dwordx4 v130, s[66:67]
	s_mov_b32 m0, s81
	s_nop 0
	global_load_lds_dwordx4 v134, s[66:67]
	s_mov_b32 m0, s83
	s_nop 0
	global_load_lds_dwordx4 v130, s[68:69]
	s_mov_b32 m0, s82
	s_nop 0
	global_load_lds_dwordx4 v134, s[68:69]
	s_add_u32 s100, s56, 0x80
	s_addc_u32 s101, s57, 0
	s_mov_b32 m0, s27
	s_nop 0
	global_load_lds_dwordx4 v128, s[56:57]
	s_mov_b32 m0, s40
	s_nop 0
	global_load_lds_dwordx4 v132, s[56:57]
	s_waitcnt vmcnt(8)
	s_waitcnt lgkmcnt(0)
	s_barrier
; #define PG8_STAGE(bufoff, gbase, voff) do { _Pragma("unroll") for (int _i = 0; _i < 2; ++_i) \
;         __builtin_amdgcn_global_load_lds((const unsigned*)((const char*)(gbase) + (voff)[_i]), (LAS unsigned*)(lds + (bufoff) + ldsw + _i * 8192), 16, 0, 0); } while (0)
; #define PG8_LDA(dst, b, h) do { _Pragma("unroll") for (int m = 0; m < 4; ++m) _Pragma("unroll") for (int k = 0; k < 2; ++k) dst[m][k] = *(const LAS bf16x8*)(lds + PG8_SA(b, h) + aoff + m * 2048 + k * 1024); } while (0)
; #define PG8_LDB(dst, b, h) do { _Pragma("unroll") for (int n = 0; n < 2; ++n) _Pragma("unroll") for (int k = 0; k < 2; ++k) dst[n][k] = *(const LAS bf16x8*)(lds + PG8_SB(b, h) + boff + n * 2048 + k * 1024); } while (0)
; #define PG8_MMA(ai, bj, At, Bt) do { __builtin_amdgcn_s_setprio(1); _Pragma("unroll") for (int m = 0; m < 4; ++m) _Pragma("unroll") for (int n = 0; n < 2; ++n) _Pragma("unroll") for (int k = 0; k < 2; ++k) \
;         acc[ai][bj][m][n] = __builtin_amdgcn_mfma_f32_16x16x32_bf16(Bt[n][k], At[m][k], acc[ai][bj][m][n], 0, 0, 0); __builtin_amdgcn_s_setprio(0); } while (0)
; #define PG8_WAIT_V(n) asm volatile("s_waitcnt vmcnt(" #n ")" ::: "memory")
; #define PG8_WAIT_L(n) asm volatile("s_waitcnt lgkmcnt(" #n ")" ::: "memory")
; #define PG8_BAR __builtin_amdgcn_s_barrier()
; #define PG8_SCHED __builtin_amdgcn_sched_barrier(0)
; DI void gemm_phase(LAS unsigned char* lds, const Gemm g, const StaticOrder& S, const Epi& E) {
;     ...
;             PG8_WAIT_V(8); PG8_WAIT_L(0); PG8_BAR; PG8_MMA(1, 0, At, B0); PG8_MMA(1, 1, At, B1); PG8_BAR; PG8_SCHED;
;             PG8_LDB(B0, 1, 0); PG8_LDB(B1, 1, 1); PG8_SCHED; PG8_LDA(At, 1, 0); PG8_STAGE(PG8_SA(0, 1), a2 + hsA, voffA);
;             PG8_WAIT_V(8); PG8_WAIT_L(0); PG8_BAR; PG8_MMA(0, 0, At, B0); PG8_MMA(0, 1, At, B1); PG8_BAR; PG8_SCHED;
	s_setprio 1
	s_waitcnt lgkmcnt(0)
	v_mfma_f32_16x16x32_bf16 v[60:63], v[140:143], v[186:189], v[60:63]
	v_mfma_f32_16x16x32_bf16 v[60:63], v[152:155], v[190:193], v[60:63]
	v_mfma_f32_16x16x32_bf16 v[56:59], v[160:163], v[190:193], v[56:59]
	v_mfma_f32_16x16x32_bf16 v[56:59], v[156:159], v[186:189], v[56:59]
	v_mfma_f32_16x16x32_bf16 v[40:43], v[156:159], v[194:197], v[40:43]
	v_mfma_f32_16x16x32_bf16 v[40:43], v[160:163], v[198:201], v[40:43]
	v_mfma_f32_16x16x32_bf16 v[44:47], v[152:155], v[198:201], v[44:47]
	v_mfma_f32_16x16x32_bf16 v[44:47], v[140:143], v[194:197], v[44:47]
	v_mfma_f32_16x16x32_bf16 v[28:31], v[140:143], v[202:205], v[28:31]
	v_mfma_f32_16x16x32_bf16 v[28:31], v[152:155], v[206:209], v[28:31]
	v_mfma_f32_16x16x32_bf16 v[24:27], v[160:163], v[206:209], v[24:27]
	v_mfma_f32_16x16x32_bf16 v[24:27], v[156:159], v[202:205], v[24:27]
	v_mfma_f32_16x16x32_bf16 v[8:11], v[156:159], v[210:213], v[8:11]
	v_mfma_f32_16x16x32_bf16 v[8:11], v[160:163], v[214:217], v[8:11]
	v_mfma_f32_16x16x32_bf16 v[12:15], v[152:155], v[214:217], v[12:15]
	v_mfma_f32_16x16x32_bf16 v[12:15], v[140:143], v[210:213], v[12:15]
	s_setprio 0
	s_setprio 1
	v_mfma_f32_16x16x32_bf16 v[52:55], v[170:173], v[186:189], v[52:55]
	v_mfma_f32_16x16x32_bf16 v[52:55], v[174:177], v[190:193], v[52:55]
	v_mfma_f32_16x16x32_bf16 v[48:51], v[182:185], v[190:193], v[48:51]
	v_mfma_f32_16x16x32_bf16 v[48:51], v[178:181], v[186:189], v[48:51]
	v_mfma_f32_16x16x32_bf16 v[32:35], v[178:181], v[194:197], v[32:35]
	v_mfma_f32_16x16x32_bf16 v[32:35], v[182:185], v[198:201], v[32:35]
	v_mfma_f32_16x16x32_bf16 v[36:39], v[174:177], v[198:201], v[36:39]
	v_mfma_f32_16x16x32_bf16 v[36:39], v[170:173], v[194:197], v[36:39]
	v_mfma_f32_16x16x32_bf16 v[20:23], v[170:173], v[202:205], v[20:23]
	v_mfma_f32_16x16x32_bf16 v[20:23], v[174:177], v[206:209], v[20:23]
	v_mfma_f32_16x16x32_bf16 v[16:19], v[182:185], v[206:209], v[16:19]
	v_mfma_f32_16x16x32_bf16 v[16:19], v[178:181], v[202:205], v[16:19]
	v_mfma_f32_16x16x32_bf16 v[0:3], v[178:181], v[210:213], v[0:3]
	v_mfma_f32_16x16x32_bf16 v[0:3], v[182:185], v[214:217], v[0:3]
	v_mfma_f32_16x16x32_bf16 v[4:7], v[174:177], v[214:217], v[4:7]
	v_mfma_f32_16x16x32_bf16 v[4:7], v[170:173], v[210:213], v[4:7]
	s_setprio 0
	s_barrier
	v_add_u32_e32 v160, s80, v147
	v_add_u32_e32 v166, s79, v147
	ds_read_b128 v[140:143], v160
	ds_read_b128 v[152:155], v160 offset:1024
	ds_read_b128 v[156:159], v160 offset:2048
	ds_read_b128 v[160:163], v160 offset:3072
	ds_read_b128 v[170:173], v166
	ds_read_b128 v[174:177], v166 offset:1024
	ds_read_b128 v[178:181], v166 offset:2048
	ds_read_b128 v[182:185], v166 offset:3072
	s_mov_b32 m0, s41
	ds_read_b128 v[186:189], v151 offset:32768
	ds_read_b128 v[190:193], v151 offset:33792
	ds_read_b128 v[194:197], v151 offset:34816
	ds_read_b128 v[198:201], v151 offset:35840
	ds_read_b128 v[202:205], v151 offset:36864
	ds_read_b128 v[206:209], v151 offset:37888
	ds_read_b128 v[210:213], v151 offset:38912
	ds_read_b128 v[214:217], v151 offset:39936
	global_load_lds_dwordx4 v128, s[54:55]
	s_mov_b32 m0, s42
	s_nop 0
	global_load_lds_dwordx4 v132, s[54:55]
	s_waitcnt vmcnt(8)
	s_waitcnt lgkmcnt(0)
	s_barrier
	s_setprio 1
	s_waitcnt lgkmcnt(0)
	v_mfma_f32_16x16x32_bf16 v[124:127], v[140:143], v[186:189], v[124:127]
	v_mfma_f32_16x16x32_bf16 v[124:127], v[152:155], v[190:193], v[124:127]
	v_mfma_f32_16x16x32_bf16 v[120:123], v[160:163], v[190:193], v[120:123]
	v_mfma_f32_16x16x32_bf16 v[120:123], v[156:159], v[186:189], v[120:123]
	v_mfma_f32_16x16x32_bf16 v[104:107], v[156:159], v[194:197], v[104:107]
	v_mfma_f32_16x16x32_bf16 v[104:107], v[160:163], v[198:201], v[104:107]
	v_mfma_f32_16x16x32_bf16 v[108:111], v[152:155], v[198:201], v[108:111]
	v_mfma_f32_16x16x32_bf16 v[108:111], v[140:143], v[194:197], v[108:111]
	v_mfma_f32_16x16x32_bf16 v[92:95], v[140:143], v[202:205], v[92:95]
	v_mfma_f32_16x16x32_bf16 v[92:95], v[152:155], v[206:209], v[92:95]
	v_mfma_f32_16x16x32_bf16 v[88:91], v[160:163], v[206:209], v[88:91]
	v_mfma_f32_16x16x32_bf16 v[88:91], v[156:159], v[202:205], v[88:91]
	v_mfma_f32_16x16x32_bf16 v[72:75], v[156:159], v[210:213], v[72:75]
	v_mfma_f32_16x16x32_bf16 v[72:75], v[160:163], v[214:217], v[72:75]
	v_mfma_f32_16x16x32_bf16 v[76:79], v[152:155], v[214:217], v[76:79]
	v_mfma_f32_16x16x32_bf16 v[76:79], v[140:143], v[210:213], v[76:79]
	s_setprio 0
	s_setprio 1
	v_mfma_f32_16x16x32_bf16 v[116:119], v[170:173], v[186:189], v[116:119]
	v_mfma_f32_16x16x32_bf16 v[116:119], v[174:177], v[190:193], v[116:119]
	v_mfma_f32_16x16x32_bf16 v[112:115], v[182:185], v[190:193], v[112:115]
	v_mfma_f32_16x16x32_bf16 v[112:115], v[178:181], v[186:189], v[112:115]
	v_mfma_f32_16x16x32_bf16 v[96:99], v[178:181], v[194:197], v[96:99]
	v_mfma_f32_16x16x32_bf16 v[96:99], v[182:185], v[198:201], v[96:99]
	v_mfma_f32_16x16x32_bf16 v[100:103], v[174:177], v[198:201], v[100:103]
	v_mfma_f32_16x16x32_bf16 v[100:103], v[170:173], v[194:197], v[100:103]
	v_mfma_f32_16x16x32_bf16 v[84:87], v[170:173], v[202:205], v[84:87]
	v_mfma_f32_16x16x32_bf16 v[84:87], v[174:177], v[206:209], v[84:87]
	v_mfma_f32_16x16x32_bf16 v[80:83], v[182:185], v[206:209], v[80:83]
	v_mfma_f32_16x16x32_bf16 v[80:83], v[178:181], v[202:205], v[80:83]
	v_mfma_f32_16x16x32_bf16 v[64:67], v[178:181], v[210:213], v[64:67]
	v_mfma_f32_16x16x32_bf16 v[64:67], v[182:185], v[214:217], v[64:67]
	v_mfma_f32_16x16x32_bf16 v[68:71], v[174:177], v[214:217], v[68:71]
	v_mfma_f32_16x16x32_bf16 v[68:71], v[170:173], v[210:213], v[68:71]
	s_setprio 0
	s_barrier
; #define PG8_STAGE(bufoff, gbase, voff) do { _Pragma("unroll") for (int _i = 0; _i < 2; ++_i) \
;         __builtin_amdgcn_global_load_lds((const unsigned*)((const char*)(gbase) + (voff)[_i]), (LAS unsigned*)(lds + (bufoff) + ldsw + _i * 8192), 16, 0, 0); } while (0)
; #define PG8_LDA(dst, b, h) do { _Pragma("unroll") for (int m = 0; m < 4; ++m) _Pragma("unroll") for (int k = 0; k < 2; ++k) dst[m][k] = *(const LAS bf16x8*)(lds + PG8_SA(b, h) + aoff + m * 2048 + k * 1024); } while (0)
; #define PG8_MMA(ai, bj, At, Bt) do { __builtin_amdgcn_s_setprio(1); _Pragma("unroll") for (int m = 0; m < 4; ++m) _Pragma("unroll") for (int n = 0; n < 2; ++n) _Pragma("unroll") for (int k = 0; k < 2; ++k) \
;         acc[ai][bj][m][n] = __builtin_amdgcn_mfma_f32_16x16x32_bf16(Bt[n][k], At[m][k], acc[ai][bj][m][n], 0, 0, 0); __builtin_amdgcn_s_setprio(0); } while (0)
; #define PG8_WAIT_V(n) asm volatile("s_waitcnt vmcnt(" #n ")" ::: "memory")
; #define PG8_WAIT_L(n) asm volatile("s_waitcnt lgkmcnt(" #n ")" ::: "memory")
; #define PG8_BAR __builtin_amdgcn_s_barrier()
; #define PG8_SCHED __builtin_amdgcn_sched_barrier(0)
; DI void gemm_phase(LAS unsigned char* lds, const Gemm g, const StaticOrder& S, const Epi& E) {
;     ...
;             PG8_LDA(At, 1, 1); PG8_STAGE(PG8_SB(1, 0), b3, voffB); PG8_STAGE(PG8_SB(1, 1), b3 + hsB, voffB); PG8_STAGE(PG8_SA(1, 0), a3, voffA);
;             PG8_WAIT_V(8); PG8_WAIT_L(0); PG8_BAR; PG8_MMA(1, 0, At, B0); PG8_MMA(1, 1, At, B1); PG8_BAR; PG8_SCHED;
;         }
;         if (wr == 0) PG8_BAR;
	s_mov_b32 m0, s78
	ds_read_b128 v[186:189], v151 offset:49152
	ds_read_b128 v[190:193], v151 offset:50176
	ds_read_b128 v[194:197], v151 offset:51200
	ds_read_b128 v[198:201], v151 offset:52224
	ds_read_b128 v[202:205], v151 offset:53248
	ds_read_b128 v[206:209], v151 offset:54272
	ds_read_b128 v[210:213], v151 offset:55296
	ds_read_b128 v[214:217], v151 offset:56320
	global_load_lds_dwordx4 v130, s[98:99]
	s_mov_b32 m0, s47
	s_nop 0
	global_load_lds_dwordx4 v134, s[98:99]
	s_mov_b32 m0, s77
	s_nop 0
	global_load_lds_dwordx4 v130, s[34:35]
	s_mov_b32 m0, s46
	s_nop 0
	global_load_lds_dwordx4 v134, s[34:35]
	s_mov_b32 m0, s48
	s_nop 0
	global_load_lds_dwordx4 v128, s[100:101]
	s_mov_b32 m0, s49
	s_nop 0
	global_load_lds_dwordx4 v132, s[100:101]
	s_waitcnt vmcnt(8)
	s_waitcnt lgkmcnt(0)
	s_barrier
	s_setprio 1
	s_waitcnt lgkmcnt(0)
	v_mfma_f32_16x16x32_bf16 v[60:63], v[140:143], v[186:189], v[60:63]
	v_mfma_f32_16x16x32_bf16 v[60:63], v[152:155], v[190:193], v[60:63]
	v_mfma_f32_16x16x32_bf16 v[56:59], v[160:163], v[190:193], v[56:59]
	v_mfma_f32_16x16x32_bf16 v[56:59], v[156:159], v[186:189], v[56:59]
	v_mfma_f32_16x16x32_bf16 v[40:43], v[156:159], v[194:197], v[40:43]
	v_mfma_f32_16x16x32_bf16 v[40:43], v[160:163], v[198:201], v[40:43]
	v_mfma_f32_16x16x32_bf16 v[44:47], v[152:155], v[198:201], v[44:47]
	v_mfma_f32_16x16x32_bf16 v[44:47], v[140:143], v[194:197], v[44:47]
	v_mfma_f32_16x16x32_bf16 v[28:31], v[140:143], v[202:205], v[28:31]
	v_mfma_f32_16x16x32_bf16 v[28:31], v[152:155], v[206:209], v[28:31]
	v_mfma_f32_16x16x32_bf16 v[24:27], v[160:163], v[206:209], v[24:27]
	v_mfma_f32_16x16x32_bf16 v[24:27], v[156:159], v[202:205], v[24:27]
	v_mfma_f32_16x16x32_bf16 v[8:11], v[156:159], v[210:213], v[8:11]
	v_mfma_f32_16x16x32_bf16 v[8:11], v[160:163], v[214:217], v[8:11]
	v_mfma_f32_16x16x32_bf16 v[12:15], v[152:155], v[214:217], v[12:15]
	v_mfma_f32_16x16x32_bf16 v[12:15], v[140:143], v[210:213], v[12:15]
	s_setprio 0
	s_setprio 1
	v_mfma_f32_16x16x32_bf16 v[52:55], v[170:173], v[186:189], v[52:55]
	v_mfma_f32_16x16x32_bf16 v[52:55], v[174:177], v[190:193], v[52:55]
	v_mfma_f32_16x16x32_bf16 v[48:51], v[182:185], v[190:193], v[48:51]
	v_mfma_f32_16x16x32_bf16 v[48:51], v[178:181], v[186:189], v[48:51]
	v_mfma_f32_16x16x32_bf16 v[32:35], v[178:181], v[194:197], v[32:35]
	v_mfma_f32_16x16x32_bf16 v[32:35], v[182:185], v[198:201], v[32:35]
	v_mfma_f32_16x16x32_bf16 v[36:39], v[174:177], v[198:201], v[36:39]
	v_mfma_f32_16x16x32_bf16 v[36:39], v[170:173], v[194:197], v[36:39]
	v_mfma_f32_16x16x32_bf16 v[20:23], v[170:173], v[202:205], v[20:23]
	v_mfma_f32_16x16x32_bf16 v[20:23], v[174:177], v[206:209], v[20:23]
	v_mfma_f32_16x16x32_bf16 v[16:19], v[182:185], v[206:209], v[16:19]
	v_mfma_f32_16x16x32_bf16 v[16:19], v[178:181], v[202:205], v[16:19]
	v_mfma_f32_16x16x32_bf16 v[0:3], v[178:181], v[210:213], v[0:3]
	v_mfma_f32_16x16x32_bf16 v[0:3], v[182:185], v[214:217], v[0:3]
	v_mfma_f32_16x16x32_bf16 v[4:7], v[174:177], v[214:217], v[4:7]
	v_mfma_f32_16x16x32_bf16 v[4:7], v[170:173], v[210:213], v[4:7]
	s_setprio 0
	s_barrier
	s_movk_i32 s46, 0x100
	s_andn2_b64 vcc, exec, s[4:5]
	s_mov_b64 s[34:35], -1
	s_mov_b64 s[4:5], 0
	s_cbranch_vccz .LBB0_461
	s_and_b64 vcc, exec, s[16:17]
	s_cbranch_vccz .LBB0_464
	s_barrier

; #define PG8_STAGE(bufoff, gbase, voff) do { _Pragma("unroll") for (int _i = 0; _i < 2; ++_i) \
;         __builtin_amdgcn_global_load_lds((const unsigned*)((const char*)(gbase) + (voff)[_i]), (LAS unsigned*)(lds + (bufoff) + ldsw + _i * 8192), 16, 0, 0); } while (0)
; #define PG8_LDA(dst, b, h) do { _Pragma("unroll") for (int m = 0; m < 4; ++m) _Pragma("unroll") for (int k = 0; k < 2; ++k) dst[m][k] = *(const LAS bf16x8*)(lds + PG8_SA(b, h) + aoff + m * 2048 + k * 1024); } while (0)
; #define PG8_LDB(dst, b, h) do { _Pragma("unroll") for (int n = 0; n < 2; ++n) _Pragma("unroll") for (int k = 0; k < 2; ++k) dst[n][k] = *(const LAS bf16x8*)(lds + PG8_SB(b, h) + boff + n * 2048 + k * 1024); } while (0)
; #define PG8_MMA(ai, bj, At, Bt) do { __builtin_amdgcn_s_setprio(1); _Pragma("unroll") for (int m = 0; m < 4; ++m) _Pragma("unroll") for (int n = 0; n < 2; ++n) _Pragma("unroll") for (int k = 0; k < 2; ++k) \
;         acc[ai][bj][m][n] = __builtin_amdgcn_mfma_f32_16x16x32_bf16(Bt[n][k], At[m][k], acc[ai][bj][m][n], 0, 0, 0); __builtin_amdgcn_s_setprio(0); } while (0)
; #define PG8_WAIT_V(n) asm volatile("s_waitcnt vmcnt(" #n ")" ::: "memory")
; #define PG8_WAIT_L(n) asm volatile("s_waitcnt lgkmcnt(" #n ")" ::: "memory")
; #define PG8_BAR __builtin_amdgcn_s_barrier()
; #define PG8_SCHED __builtin_amdgcn_sched_barrier(0)
; DI void gemm_phase(LAS unsigned char* lds, const Gemm g, const StaticOrder& S, const Epi& E) {
;     ...
;         for (int t = 0; t < nt; t += 2) {
;             const bool last = (t == nt - 2);
;             const char* a1 = cA + (size_t)(t + 1) * kstep;
;             const char* a2 = last ? nA : cA + (size_t)(t + 2) * kstep; const char* b2 = last ? nB : cB + (size_t)(t + 2) * kstep;
;             const char* a3 = a2 + kstep; const char* b3 = b2 + kstep;
;             PG8_LDB(B0, 0, 0); PG8_LDB(B1, 0, 1); PG8_SCHED; PG8_LDA(At, 0, 0); PG8_STAGE(PG8_SA(1, 1), a1 + hsA, voffA);
;             PG8_WAIT_V(8); PG8_WAIT_L(0); PG8_BAR; PG8_MMA(0, 0, At, B0); PG8_MMA(0, 1, At, B1); PG8_BAR; PG8_SCHED;
;             PG8_LDA(At, 0, 1); PG8_STAGE(PG8_SB(0, 0), b2, voffB); PG8_STAGE(PG8_SB(0, 1), b2 + hsB, voffB); PG8_STAGE(PG8_SA(0, 0), a2, voffA);
;             PG8_WAIT_V(8); PG8_WAIT_L(0); PG8_BAR; PG8_MMA(1, 0, At, B0); PG8_MMA(1, 1, At, B1); PG8_BAR; PG8_SCHED;
.LBB0_936:
	ds_read_b128 v[144:147], v155
	ds_read_b128 v[148:151], v155 offset:1024
	ds_read_b128 v[160:163], v155 offset:2048
	ds_read_b128 v[170:173], v155 offset:3072
	ds_read_b128 v[174:177], v156
	ds_read_b128 v[178:181], v156 offset:1024
	ds_read_b128 v[182:185], v156 offset:2048
	ds_read_b128 v[186:189], v156 offset:3072
	s_add_u32 s34, s30, 0xfff80080
	s_addc_u32 s35, s31, -1
	s_cmp_eq_u32 s51, 28
	s_cselect_b32 s37, s21, s35
	s_cselect_b32 s36, s27, s34
	s_cselect_b32 s35, s19, s50
	s_cselect_b32 s34, s48, s49
	s_add_i32 m0, s13, 0xc000
	ds_read_b128 v[190:193], v157
	ds_read_b128 v[194:197], v157 offset:1024
	ds_read_b128 v[198:201], v157 offset:2048
	ds_read_b128 v[202:205], v157 offset:3072
	ds_read_b128 v[206:209], v157 offset:4096
	ds_read_b128 v[210:213], v157 offset:5120
	ds_read_b128 v[214:217], v157 offset:6144
	ds_read_b128 v[218:221], v157 offset:7168
	global_load_lds_dwordx4 v136, s[30:31]
	s_add_i32 m0, s13, 0xe000
	s_nop 0
	global_load_lds_dwordx4 v138, s[30:31]
	s_waitcnt vmcnt(8)
	s_waitcnt lgkmcnt(0)
	s_barrier
	s_setprio 1
	s_waitcnt lgkmcnt(0)
	v_mfma_f32_16x16x32_bf16 v[124:127], v[144:147], v[190:193], v[124:127]
	v_mfma_f32_16x16x32_bf16 v[124:127], v[148:151], v[194:197], v[124:127]
	v_mfma_f32_16x16x32_bf16 v[120:123], v[170:173], v[194:197], v[120:123]
	v_mfma_f32_16x16x32_bf16 v[120:123], v[160:163], v[190:193], v[120:123]
	v_mfma_f32_16x16x32_bf16 v[104:107], v[160:163], v[198:201], v[104:107]
	v_mfma_f32_16x16x32_bf16 v[104:107], v[170:173], v[202:205], v[104:107]
	v_mfma_f32_16x16x32_bf16 v[108:111], v[148:151], v[202:205], v[108:111]
	v_mfma_f32_16x16x32_bf16 v[108:111], v[144:147], v[198:201], v[108:111]
	v_mfma_f32_16x16x32_bf16 v[92:95], v[144:147], v[206:209], v[92:95]
	v_mfma_f32_16x16x32_bf16 v[92:95], v[148:151], v[210:213], v[92:95]
	v_mfma_f32_16x16x32_bf16 v[88:91], v[170:173], v[210:213], v[88:91]
	v_mfma_f32_16x16x32_bf16 v[88:91], v[160:163], v[206:209], v[88:91]
	v_mfma_f32_16x16x32_bf16 v[72:75], v[160:163], v[214:217], v[72:75]
	v_mfma_f32_16x16x32_bf16 v[72:75], v[170:173], v[218:221], v[72:75]
	v_mfma_f32_16x16x32_bf16 v[76:79], v[148:151], v[218:221], v[76:79]
	v_mfma_f32_16x16x32_bf16 v[76:79], v[144:147], v[214:217], v[76:79]
	s_setprio 0
	s_setprio 1
	v_mfma_f32_16x16x32_bf16 v[116:119], v[174:177], v[190:193], v[116:119]
	v_mfma_f32_16x16x32_bf16 v[116:119], v[178:181], v[194:197], v[116:119]
	v_mfma_f32_16x16x32_bf16 v[112:115], v[186:189], v[194:197], v[112:115]
	v_mfma_f32_16x16x32_bf16 v[112:115], v[182:185], v[190:193], v[112:115]
	v_mfma_f32_16x16x32_bf16 v[96:99], v[182:185], v[198:201], v[96:99]
	v_mfma_f32_16x16x32_bf16 v[96:99], v[186:189], v[202:205], v[96:99]
	v_mfma_f32_16x16x32_bf16 v[100:103], v[178:181], v[202:205], v[100:103]
	v_mfma_f32_16x16x32_bf16 v[100:103], v[174:177], v[198:201], v[100:103]
	v_mfma_f32_16x16x32_bf16 v[84:87], v[174:177], v[206:209], v[84:87]
	v_mfma_f32_16x16x32_bf16 v[84:87], v[178:181], v[210:213], v[84:87]
	v_mfma_f32_16x16x32_bf16 v[80:83], v[186:189], v[210:213], v[80:83]
	v_mfma_f32_16x16x32_bf16 v[80:83], v[182:185], v[206:209], v[80:83]
	v_mfma_f32_16x16x32_bf16 v[64:67], v[182:185], v[214:217], v[64:67]
	v_mfma_f32_16x16x32_bf16 v[64:67], v[186:189], v[218:221], v[64:67]
	v_mfma_f32_16x16x32_bf16 v[68:71], v[178:181], v[218:221], v[68:71]
	v_mfma_f32_16x16x32_bf16 v[68:71], v[174:177], v[214:217], v[68:71]
	s_setprio 0
	s_barrier
	s_add_i32 s46, s42, s12
	s_add_u32 s98, s34, 0x80
	s_addc_u32 s99, s35, 0
	s_mov_b32 m0, s46
	ds_read_b128 v[190:193], v157 offset:16384
	ds_read_b128 v[194:197], v157 offset:17408
	ds_read_b128 v[198:201], v157 offset:18432
	ds_read_b128 v[202:205], v157 offset:19456
	ds_read_b128 v[206:209], v157 offset:20480
	ds_read_b128 v[210:213], v157 offset:21504
	ds_read_b128 v[214:217], v157 offset:22528
	ds_read_b128 v[218:221], v157 offset:23552
	global_load_lds_dwordx4 v130, s[34:35]
	s_add_i32 m0, s46, 0x2000
	s_add_u32 s46, s34, 0x80000
	s_addc_u32 s47, s35, 0
	s_add_i32 s52, s43, s12
	global_load_lds_dwordx4 v134, s[34:35]
	s_mov_b32 m0, s52
	s_nop 0
	global_load_lds_dwordx4 v130, s[46:47]
	s_add_i32 m0, s52, 0x2000
	s_nop 0
	global_load_lds_dwordx4 v134, s[46:47]
	s_add_u32 s100, s36, 0x80
	s_addc_u32 s101, s37, 0
	s_mov_b32 m0, s13
	s_nop 0
	global_load_lds_dwordx4 v128, s[36:37]
	s_mov_b32 m0, s29
	s_nop 0
	global_load_lds_dwordx4 v132, s[36:37]
	s_waitcnt vmcnt(8)
	s_waitcnt lgkmcnt(0)
	s_barrier
	s_setprio 1
	s_waitcnt lgkmcnt(0)
	v_mfma_f32_16x16x32_bf16 v[60:63], v[144:147], v[190:193], v[60:63]
	v_mfma_f32_16x16x32_bf16 v[60:63], v[148:151], v[194:197], v[60:63]
	v_mfma_f32_16x16x32_bf16 v[56:59], v[170:173], v[194:197], v[56:59]
	v_mfma_f32_16x16x32_bf16 v[56:59], v[160:163], v[190:193], v[56:59]
	v_mfma_f32_16x16x32_bf16 v[40:43], v[160:163], v[198:201], v[40:43]
	v_mfma_f32_16x16x32_bf16 v[40:43], v[170:173], v[202:205], v[40:43]
	v_mfma_f32_16x16x32_bf16 v[44:47], v[148:151], v[202:205], v[44:47]
	v_mfma_f32_16x16x32_bf16 v[44:47], v[144:147], v[198:201], v[44:47]
	v_mfma_f32_16x16x32_bf16 v[28:31], v[144:147], v[206:209], v[28:31]
	v_mfma_f32_16x16x32_bf16 v[28:31], v[148:151], v[210:213], v[28:31]
	v_mfma_f32_16x16x32_bf16 v[24:27], v[170:173], v[210:213], v[24:27]
	v_mfma_f32_16x16x32_bf16 v[24:27], v[160:163], v[206:209], v[24:27]
	v_mfma_f32_16x16x32_bf16 v[8:11], v[160:163], v[214:217], v[8:11]
	v_mfma_f32_16x16x32_bf16 v[8:11], v[170:173], v[218:221], v[8:11]
	v_mfma_f32_16x16x32_bf16 v[12:15], v[148:151], v[218:221], v[12:15]
	v_mfma_f32_16x16x32_bf16 v[12:15], v[144:147], v[214:217], v[12:15]
	s_setprio 0
	s_setprio 1
	v_mfma_f32_16x16x32_bf16 v[52:55], v[174:177], v[190:193], v[52:55]
	v_mfma_f32_16x16x32_bf16 v[52:55], v[178:181], v[194:197], v[52:55]
	v_mfma_f32_16x16x32_bf16 v[48:51], v[186:189], v[194:197], v[48:51]
	v_mfma_f32_16x16x32_bf16 v[48:51], v[182:185], v[190:193], v[48:51]
	v_mfma_f32_16x16x32_bf16 v[32:35], v[182:185], v[198:201], v[32:35]
	v_mfma_f32_16x16x32_bf16 v[32:35], v[186:189], v[202:205], v[32:35]
	v_mfma_f32_16x16x32_bf16 v[36:39], v[178:181], v[202:205], v[36:39]
	v_mfma_f32_16x16x32_bf16 v[36:39], v[174:177], v[198:201], v[36:39]
	v_mfma_f32_16x16x32_bf16 v[20:23], v[174:177], v[206:209], v[20:23]
	v_mfma_f32_16x16x32_bf16 v[20:23], v[178:181], v[210:213], v[20:23]
	v_mfma_f32_16x16x32_bf16 v[16:19], v[186:189], v[210:213], v[16:19]
	v_mfma_f32_16x16x32_bf16 v[16:19], v[182:185], v[206:209], v[16:19]
	v_mfma_f32_16x16x32_bf16 v[0:3], v[182:185], v[214:217], v[0:3]
	v_mfma_f32_16x16x32_bf16 v[0:3], v[186:189], v[218:221], v[0:3]
	v_mfma_f32_16x16x32_bf16 v[4:7], v[178:181], v[218:221], v[4:7]
	v_mfma_f32_16x16x32_bf16 v[4:7], v[174:177], v[214:217], v[4:7]
	s_setprio 0
	s_barrier
; #define PG8_STAGE(bufoff, gbase, voff) do { _Pragma("unroll") for (int _i = 0; _i < 2; ++_i) \
;         __builtin_amdgcn_global_load_lds((const unsigned*)((const char*)(gbase) + (voff)[_i]), (LAS unsigned*)(lds + (bufoff) + ldsw + _i * 8192), 16, 0, 0); } while (0)
; #define PG8_LDA(dst, b, h) do { _Pragma("unroll") for (int m = 0; m < 4; ++m) _Pragma("unroll") for (int k = 0; k < 2; ++k) dst[m][k] = *(const LAS bf16x8*)(lds + PG8_SA(b, h) + aoff + m * 2048 + k * 1024); } while (0)
; #define PG8_LDB(dst, b, h) do { _Pragma("unroll") for (int n = 0; n < 2; ++n) _Pragma("unroll") for (int k = 0; k < 2; ++k) dst[n][k] = *(const LAS bf16x8*)(lds + PG8_SB(b, h) + boff + n * 2048 + k * 1024); } while (0)
; #define PG8_MMA(ai, bj, At, Bt) do { __builtin_amdgcn_s_setprio(1); _Pragma("unroll") for (int m = 0; m < 4; ++m) _Pragma("unroll") for (int n = 0; n < 2; ++n) _Pragma("unroll") for (int k = 0; k < 2; ++k) \
;         acc[ai][bj][m][n] = __builtin_amdgcn_mfma_f32_16x16x32_bf16(Bt[n][k], At[m][k], acc[ai][bj][m][n], 0, 0, 0); __builtin_amdgcn_s_setprio(0); } while (0)
; #define PG8_WAIT_V(n) asm volatile("s_waitcnt vmcnt(" #n ")" ::: "memory")
; #define PG8_WAIT_L(n) asm volatile("s_waitcnt lgkmcnt(" #n ")" ::: "memory")
; #define PG8_BAR __builtin_amdgcn_s_barrier()
; #define PG8_SCHED __builtin_amdgcn_sched_barrier(0)
; DI void gemm_phase(LAS unsigned char* lds, const Gemm g, const StaticOrder& S, const Epi& E) {
;     ...
;             PG8_LDB(B0, 1, 0); PG8_LDB(B1, 1, 1); PG8_SCHED; PG8_LDA(At, 1, 0); PG8_STAGE(PG8_SA(0, 1), a2 + hsA, voffA);
;             PG8_WAIT_V(8); PG8_WAIT_L(0); PG8_BAR; PG8_MMA(0, 0, At, B0); PG8_MMA(0, 1, At, B1); PG8_BAR; PG8_SCHED;
;             PG8_LDA(At, 1, 1); PG8_STAGE(PG8_SB(1, 0), b3, voffB); PG8_STAGE(PG8_SB(1, 1), b3 + hsB, voffB); PG8_STAGE(PG8_SA(1, 0), a3, voffA);
;             PG8_WAIT_V(8); PG8_WAIT_L(0); PG8_BAR; PG8_MMA(1, 0, At, B0); PG8_MMA(1, 1, At, B1); PG8_BAR; PG8_SCHED;
;         }
;         if (wr == 0) PG8_BAR;
	s_add_i32 s46, 0, 0x18000
	v_add_u32_e32 v159, s46, v153
	s_add_i32 s47, 0, 0x1c000
	ds_read_b128 v[144:147], v159
	ds_read_b128 v[148:151], v159 offset:1024
	ds_read_b128 v[160:163], v159 offset:2048
	ds_read_b128 v[170:173], v159 offset:3072
	v_add_u32_e32 v159, s47, v153
	ds_read_b128 v[174:177], v159
	ds_read_b128 v[178:181], v159 offset:1024
	ds_read_b128 v[182:185], v159 offset:2048
	ds_read_b128 v[186:189], v159 offset:3072
	s_add_u32 s36, s36, 0x80000
	s_addc_u32 s37, s37, 0
	s_mov_b32 m0, s33
	ds_read_b128 v[190:193], v157 offset:32768
	ds_read_b128 v[194:197], v157 offset:33792
	ds_read_b128 v[198:201], v157 offset:34816
	ds_read_b128 v[202:205], v157 offset:35840
	ds_read_b128 v[206:209], v157 offset:36864
	ds_read_b128 v[210:213], v157 offset:37888
	ds_read_b128 v[214:217], v157 offset:38912
	ds_read_b128 v[218:221], v157 offset:39936
	global_load_lds_dwordx4 v128, s[36:37]
	s_mov_b32 m0, s38
	s_nop 0
	global_load_lds_dwordx4 v132, s[36:37]
	s_waitcnt vmcnt(8)
	s_waitcnt lgkmcnt(0)
	s_barrier
	s_setprio 1
	s_waitcnt lgkmcnt(0)
	v_mfma_f32_16x16x32_bf16 v[124:127], v[144:147], v[190:193], v[124:127]
	v_mfma_f32_16x16x32_bf16 v[124:127], v[148:151], v[194:197], v[124:127]
	v_mfma_f32_16x16x32_bf16 v[120:123], v[170:173], v[194:197], v[120:123]
	v_mfma_f32_16x16x32_bf16 v[120:123], v[160:163], v[190:193], v[120:123]
	v_mfma_f32_16x16x32_bf16 v[104:107], v[160:163], v[198:201], v[104:107]
	v_mfma_f32_16x16x32_bf16 v[104:107], v[170:173], v[202:205], v[104:107]
	v_mfma_f32_16x16x32_bf16 v[108:111], v[148:151], v[202:205], v[108:111]
	v_mfma_f32_16x16x32_bf16 v[108:111], v[144:147], v[198:201], v[108:111]
	v_mfma_f32_16x16x32_bf16 v[92:95], v[144:147], v[206:209], v[92:95]
	v_mfma_f32_16x16x32_bf16 v[92:95], v[148:151], v[210:213], v[92:95]
	v_mfma_f32_16x16x32_bf16 v[88:91], v[170:173], v[210:213], v[88:91]
	v_mfma_f32_16x16x32_bf16 v[88:91], v[160:163], v[206:209], v[88:91]
	v_mfma_f32_16x16x32_bf16 v[72:75], v[160:163], v[214:217], v[72:75]
	v_mfma_f32_16x16x32_bf16 v[72:75], v[170:173], v[218:221], v[72:75]
	v_mfma_f32_16x16x32_bf16 v[76:79], v[148:151], v[218:221], v[76:79]
	v_mfma_f32_16x16x32_bf16 v[76:79], v[144:147], v[214:217], v[76:79]
	s_setprio 0
	s_setprio 1
	v_mfma_f32_16x16x32_bf16 v[116:119], v[174:177], v[190:193], v[116:119]
	v_mfma_f32_16x16x32_bf16 v[116:119], v[178:181], v[194:197], v[116:119]
	v_mfma_f32_16x16x32_bf16 v[112:115], v[186:189], v[194:197], v[112:115]
	v_mfma_f32_16x16x32_bf16 v[112:115], v[182:185], v[190:193], v[112:115]
	v_mfma_f32_16x16x32_bf16 v[96:99], v[182:185], v[198:201], v[96:99]
	v_mfma_f32_16x16x32_bf16 v[96:99], v[186:189], v[202:205], v[96:99]
	v_mfma_f32_16x16x32_bf16 v[100:103], v[178:181], v[202:205], v[100:103]
	v_mfma_f32_16x16x32_bf16 v[100:103], v[174:177], v[198:201], v[100:103]
	v_mfma_f32_16x16x32_bf16 v[84:87], v[174:177], v[206:209], v[84:87]
	v_mfma_f32_16x16x32_bf16 v[84:87], v[178:181], v[210:213], v[84:87]
	v_mfma_f32_16x16x32_bf16 v[80:83], v[186:189], v[210:213], v[80:83]
	v_mfma_f32_16x16x32_bf16 v[80:83], v[182:185], v[206:209], v[80:83]
	v_mfma_f32_16x16x32_bf16 v[64:67], v[182:185], v[214:217], v[64:67]
	v_mfma_f32_16x16x32_bf16 v[64:67], v[186:189], v[218:221], v[64:67]
	v_mfma_f32_16x16x32_bf16 v[68:71], v[178:181], v[218:221], v[68:71]
	v_mfma_f32_16x16x32_bf16 v[68:71], v[174:177], v[214:217], v[68:71]
	s_setprio 0
	s_barrier
	s_add_i32 s36, s46, s12
	s_mov_b32 m0, s36
	ds_read_b128 v[190:193], v157 offset:49152
	ds_read_b128 v[194:197], v157 offset:50176
	ds_read_b128 v[198:201], v157 offset:51200
	ds_read_b128 v[202:205], v157 offset:52224
	ds_read_b128 v[206:209], v157 offset:53248
	ds_read_b128 v[210:213], v157 offset:54272
	ds_read_b128 v[214:217], v157 offset:55296
	ds_read_b128 v[218:221], v157 offset:56320
	global_load_lds_dwordx4 v130, s[98:99]
	s_add_i32 m0, s36, 0x2000
	s_add_u32 s34, s34, 0x80080
	s_addc_u32 s35, s35, 0
	s_add_i32 s36, s47, s12
	global_load_lds_dwordx4 v134, s[98:99]
	s_mov_b32 m0, s36
	s_nop 0
	global_load_lds_dwordx4 v130, s[34:35]
	s_add_i32 m0, s36, 0x2000
	s_nop 0
	global_load_lds_dwordx4 v134, s[34:35]
	s_mov_b32 m0, s40
	s_nop 0
	global_load_lds_dwordx4 v128, s[100:101]
	s_mov_b32 m0, s41
	s_nop 0
	global_load_lds_dwordx4 v132, s[100:101]
	s_waitcnt vmcnt(8)
	s_waitcnt lgkmcnt(0)
	s_barrier
	s_setprio 1
	s_waitcnt lgkmcnt(0)
	v_mfma_f32_16x16x32_bf16 v[60:63], v[144:147], v[190:193], v[60:63]
	v_mfma_f32_16x16x32_bf16 v[60:63], v[148:151], v[194:197], v[60:63]
	v_mfma_f32_16x16x32_bf16 v[56:59], v[170:173], v[194:197], v[56:59]
	v_mfma_f32_16x16x32_bf16 v[56:59], v[160:163], v[190:193], v[56:59]
	v_mfma_f32_16x16x32_bf16 v[40:43], v[160:163], v[198:201], v[40:43]
	v_mfma_f32_16x16x32_bf16 v[40:43], v[170:173], v[202:205], v[40:43]
	v_mfma_f32_16x16x32_bf16 v[44:47], v[148:151], v[202:205], v[44:47]
	v_mfma_f32_16x16x32_bf16 v[44:47], v[144:147], v[198:201], v[44:47]
	v_mfma_f32_16x16x32_bf16 v[28:31], v[144:147], v[206:209], v[28:31]
	v_mfma_f32_16x16x32_bf16 v[28:31], v[148:151], v[210:213], v[28:31]
	v_mfma_f32_16x16x32_bf16 v[24:27], v[170:173], v[210:213], v[24:27]
	v_mfma_f32_16x16x32_bf16 v[24:27], v[160:163], v[206:209], v[24:27]
	v_mfma_f32_16x16x32_bf16 v[8:11], v[160:163], v[214:217], v[8:11]
	v_mfma_f32_16x16x32_bf16 v[8:11], v[170:173], v[218:221], v[8:11]
	v_mfma_f32_16x16x32_bf16 v[12:15], v[148:151], v[218:221], v[12:15]
	v_mfma_f32_16x16x32_bf16 v[12:15], v[144:147], v[214:217], v[12:15]
	s_setprio 0
	s_setprio 1
	v_mfma_f32_16x16x32_bf16 v[52:55], v[174:177], v[190:193], v[52:55]
	v_mfma_f32_16x16x32_bf16 v[52:55], v[178:181], v[194:197], v[52:55]
	v_mfma_f32_16x16x32_bf16 v[48:51], v[186:189], v[194:197], v[48:51]
	v_mfma_f32_16x16x32_bf16 v[48:51], v[182:185], v[190:193], v[48:51]
	v_mfma_f32_16x16x32_bf16 v[32:35], v[182:185], v[198:201], v[32:35]
	v_mfma_f32_16x16x32_bf16 v[32:35], v[186:189], v[202:205], v[32:35]
	v_mfma_f32_16x16x32_bf16 v[36:39], v[178:181], v[202:205], v[36:39]
	v_mfma_f32_16x16x32_bf16 v[36:39], v[174:177], v[198:201], v[36:39]
	v_mfma_f32_16x16x32_bf16 v[20:23], v[174:177], v[206:209], v[20:23]
	v_mfma_f32_16x16x32_bf16 v[20:23], v[178:181], v[210:213], v[20:23]
	v_mfma_f32_16x16x32_bf16 v[16:19], v[186:189], v[210:213], v[16:19]
	v_mfma_f32_16x16x32_bf16 v[16:19], v[182:185], v[206:209], v[16:19]
	v_mfma_f32_16x16x32_bf16 v[0:3], v[182:185], v[214:217], v[0:3]
	v_mfma_f32_16x16x32_bf16 v[0:3], v[186:189], v[218:221], v[0:3]
	v_mfma_f32_16x16x32_bf16 v[4:7], v[178:181], v[218:221], v[4:7]
	v_mfma_f32_16x16x32_bf16 v[4:7], v[174:177], v[214:217], v[4:7]
	s_setprio 0
	s_barrier
	s_add_i32 s51, s51, 2
	s_add_u32 s30, s30, 0x100
	s_addc_u32 s31, s31, 0
	s_add_u32 s49, s49, 0x100
	s_addc_u32 s50, s50, 0
	s_cmp_gt_u32 s51, 29
	s_cbranch_scc0 .LBB0_936
	s_and_b64 vcc, exec, s[16:17]
	s_cbranch_vccz .LBB0_939
	s_barrier

; #define PG8_STAGE(bufoff, gbase, voff) do { _Pragma("unroll") for (int _i = 0; _i < 2; ++_i) \
;         __builtin_amdgcn_global_load_lds((const unsigned*)((const char*)(gbase) + (voff)[_i]), (LAS unsigned*)(lds + (bufoff) + ldsw + _i * 8192), 16, 0, 0); } while (0)
; #define PG8_LDA(dst, b, h) do { _Pragma("unroll") for (int m = 0; m < 4; ++m) _Pragma("unroll") for (int k = 0; k < 2; ++k) dst[m][k] = *(const LAS bf16x8*)(lds + PG8_SA(b, h) + aoff + m * 2048 + k * 1024); } while (0)
; #define PG8_LDB(dst, b, h) do { _Pragma("unroll") for (int n = 0; n < 2; ++n) _Pragma("unroll") for (int k = 0; k < 2; ++k) dst[n][k] = *(const LAS bf16x8*)(lds + PG8_SB(b, h) + boff + n * 2048 + k * 1024); } while (0)
; #define PG8_MMA(ai, bj, At, Bt) do { __builtin_amdgcn_s_setprio(1); _Pragma("unroll") for (int m = 0; m < 4; ++m) _Pragma("unroll") for (int n = 0; n < 2; ++n) _Pragma("unroll") for (int k = 0; k < 2; ++k) \
;         acc[ai][bj][m][n] = __builtin_amdgcn_mfma_f32_16x16x32_bf16(Bt[n][k], At[m][k], acc[ai][bj][m][n], 0, 0, 0); __builtin_amdgcn_s_setprio(0); } while (0)
; #define PG8_WAIT_V(n) asm volatile("s_waitcnt vmcnt(" #n ")" ::: "memory")
; #define PG8_WAIT_L(n) asm volatile("s_waitcnt lgkmcnt(" #n ")" ::: "memory")
; #define PG8_BAR __builtin_amdgcn_s_barrier()
; #define PG8_SCHED __builtin_amdgcn_sched_barrier(0)
; DI void gemm_phase(LAS unsigned char* lds, const Gemm g, const StaticOrder& S, const Epi& E) {
;     ...
;         for (int t = 0; t < nt; t += 2) {
;             const bool last = (t == nt - 2);
;             const char* a1 = cA + (size_t)(t + 1) * kstep;
;             const char* a2 = last ? nA : cA + (size_t)(t + 2) * kstep; const char* b2 = last ? nB : cB + (size_t)(t + 2) * kstep;
;             const char* a3 = a2 + kstep; const char* b3 = b2 + kstep;
;             PG8_LDB(B0, 0, 0); PG8_LDB(B1, 0, 1); PG8_SCHED; PG8_LDA(At, 0, 0); PG8_STAGE(PG8_SA(1, 1), a1 + hsA, voffA);
;             PG8_WAIT_V(8); PG8_WAIT_L(0); PG8_BAR; PG8_MMA(0, 0, At, B0); PG8_MMA(0, 1, At, B1); PG8_BAR; PG8_SCHED;
;             PG8_LDA(At, 0, 1); PG8_STAGE(PG8_SB(0, 0), b2, voffB); PG8_STAGE(PG8_SB(0, 1), b2 + hsB, voffB); PG8_STAGE(PG8_SA(0, 0), a2, voffA);
;             PG8_WAIT_V(8); PG8_WAIT_L(0); PG8_BAR; PG8_MMA(1, 0, At, B0); PG8_MMA(1, 1, At, B1); PG8_BAR; PG8_SCHED;
.LBB0_1020:
	ds_read_b128 v[144:147], v155
	ds_read_b128 v[148:151], v155 offset:1024
	ds_read_b128 v[160:163], v155 offset:2048
	ds_read_b128 v[170:173], v155 offset:3072
	ds_read_b128 v[174:177], v156
	ds_read_b128 v[178:181], v156 offset:1024
	ds_read_b128 v[182:185], v156 offset:2048
	ds_read_b128 v[186:189], v156 offset:3072
	s_add_u32 s26, s24, 0xfff80080
	s_addc_u32 s27, s25, -1
	s_cmp_eq_u32 s49, 28
	s_cselect_b32 s29, s17, s27
	s_cselect_b32 s28, s41, s26
	s_cselect_b32 s27, s15, s48
	s_cselect_b32 s26, s42, s43
	s_add_i32 m0, s23, 0xc000
	ds_read_b128 v[190:193], v157
	ds_read_b128 v[194:197], v157 offset:1024
	ds_read_b128 v[198:201], v157 offset:2048
	ds_read_b128 v[202:205], v157 offset:3072
	ds_read_b128 v[206:209], v157 offset:4096
	ds_read_b128 v[210:213], v157 offset:5120
	ds_read_b128 v[214:217], v157 offset:6144
	ds_read_b128 v[218:221], v157 offset:7168
	global_load_lds_dwordx4 v136, s[24:25]
	s_add_i32 m0, s23, 0xe000
	s_nop 0
	global_load_lds_dwordx4 v138, s[24:25]
	s_waitcnt vmcnt(8)
	s_waitcnt lgkmcnt(0)
	s_barrier
	s_setprio 1
	s_waitcnt lgkmcnt(0)
	v_mfma_f32_16x16x32_bf16 v[124:127], v[144:147], v[190:193], v[124:127]
	v_mfma_f32_16x16x32_bf16 v[124:127], v[148:151], v[194:197], v[124:127]
	v_mfma_f32_16x16x32_bf16 v[120:123], v[170:173], v[194:197], v[120:123]
	v_mfma_f32_16x16x32_bf16 v[120:123], v[160:163], v[190:193], v[120:123]
	v_mfma_f32_16x16x32_bf16 v[104:107], v[160:163], v[198:201], v[104:107]
	v_mfma_f32_16x16x32_bf16 v[104:107], v[170:173], v[202:205], v[104:107]
	v_mfma_f32_16x16x32_bf16 v[108:111], v[148:151], v[202:205], v[108:111]
	v_mfma_f32_16x16x32_bf16 v[108:111], v[144:147], v[198:201], v[108:111]
	v_mfma_f32_16x16x32_bf16 v[92:95], v[144:147], v[206:209], v[92:95]
	v_mfma_f32_16x16x32_bf16 v[92:95], v[148:151], v[210:213], v[92:95]
	v_mfma_f32_16x16x32_bf16 v[88:91], v[170:173], v[210:213], v[88:91]
	v_mfma_f32_16x16x32_bf16 v[88:91], v[160:163], v[206:209], v[88:91]
	v_mfma_f32_16x16x32_bf16 v[72:75], v[160:163], v[214:217], v[72:75]
	v_mfma_f32_16x16x32_bf16 v[72:75], v[170:173], v[218:221], v[72:75]
	v_mfma_f32_16x16x32_bf16 v[76:79], v[148:151], v[218:221], v[76:79]
	v_mfma_f32_16x16x32_bf16 v[76:79], v[144:147], v[214:217], v[76:79]
	s_setprio 0
	s_setprio 1
	v_mfma_f32_16x16x32_bf16 v[116:119], v[174:177], v[190:193], v[116:119]
	v_mfma_f32_16x16x32_bf16 v[116:119], v[178:181], v[194:197], v[116:119]
	v_mfma_f32_16x16x32_bf16 v[112:115], v[186:189], v[194:197], v[112:115]
	v_mfma_f32_16x16x32_bf16 v[112:115], v[182:185], v[190:193], v[112:115]
	v_mfma_f32_16x16x32_bf16 v[96:99], v[182:185], v[198:201], v[96:99]
	v_mfma_f32_16x16x32_bf16 v[96:99], v[186:189], v[202:205], v[96:99]
	v_mfma_f32_16x16x32_bf16 v[100:103], v[178:181], v[202:205], v[100:103]
	v_mfma_f32_16x16x32_bf16 v[100:103], v[174:177], v[198:201], v[100:103]
	v_mfma_f32_16x16x32_bf16 v[84:87], v[174:177], v[206:209], v[84:87]
	v_mfma_f32_16x16x32_bf16 v[84:87], v[178:181], v[210:213], v[84:87]
	v_mfma_f32_16x16x32_bf16 v[80:83], v[186:189], v[210:213], v[80:83]
	v_mfma_f32_16x16x32_bf16 v[80:83], v[182:185], v[206:209], v[80:83]
	v_mfma_f32_16x16x32_bf16 v[64:67], v[182:185], v[214:217], v[64:67]
	v_mfma_f32_16x16x32_bf16 v[64:67], v[186:189], v[218:221], v[64:67]
	v_mfma_f32_16x16x32_bf16 v[68:71], v[178:181], v[218:221], v[68:71]
	v_mfma_f32_16x16x32_bf16 v[68:71], v[174:177], v[214:217], v[68:71]
	s_setprio 0
	s_barrier
	s_add_i32 s46, s37, s12
	s_add_u32 s98, s26, 0x80
	s_addc_u32 s99, s27, 0
	s_mov_b32 m0, s46
	ds_read_b128 v[190:193], v157 offset:16384
	ds_read_b128 v[194:197], v157 offset:17408
	ds_read_b128 v[198:201], v157 offset:18432
	ds_read_b128 v[202:205], v157 offset:19456
	ds_read_b128 v[206:209], v157 offset:20480
	ds_read_b128 v[210:213], v157 offset:21504
	ds_read_b128 v[214:217], v157 offset:22528
	ds_read_b128 v[218:221], v157 offset:23552
	global_load_lds_dwordx4 v132, s[26:27]
	s_add_i32 m0, s46, 0x2000
	s_add_u32 s46, s26, 0x80000
	s_addc_u32 s47, s27, 0
	s_add_i32 s50, s38, s12
	global_load_lds_dwordx4 v128, s[26:27]
	s_mov_b32 m0, s50
	s_nop 0
	global_load_lds_dwordx4 v132, s[46:47]
	s_add_i32 m0, s50, 0x2000
	s_nop 0
	global_load_lds_dwordx4 v128, s[46:47]
	s_add_u32 s100, s28, 0x80
	s_addc_u32 s101, s29, 0
	s_mov_b32 m0, s23
	s_nop 0
	global_load_lds_dwordx4 v134, s[28:29]
	s_mov_b32 m0, s30
	s_nop 0
	global_load_lds_dwordx4 v130, s[28:29]
	s_waitcnt vmcnt(8)
	s_waitcnt lgkmcnt(0)
	s_barrier
	s_setprio 1
	s_waitcnt lgkmcnt(0)
	v_mfma_f32_16x16x32_bf16 v[60:63], v[144:147], v[190:193], v[60:63]
	v_mfma_f32_16x16x32_bf16 v[60:63], v[148:151], v[194:197], v[60:63]
	v_mfma_f32_16x16x32_bf16 v[56:59], v[170:173], v[194:197], v[56:59]
	v_mfma_f32_16x16x32_bf16 v[56:59], v[160:163], v[190:193], v[56:59]
	v_mfma_f32_16x16x32_bf16 v[40:43], v[160:163], v[198:201], v[40:43]
	v_mfma_f32_16x16x32_bf16 v[40:43], v[170:173], v[202:205], v[40:43]
	v_mfma_f32_16x16x32_bf16 v[44:47], v[148:151], v[202:205], v[44:47]
	v_mfma_f32_16x16x32_bf16 v[44:47], v[144:147], v[198:201], v[44:47]
	v_mfma_f32_16x16x32_bf16 v[28:31], v[144:147], v[206:209], v[28:31]
	v_mfma_f32_16x16x32_bf16 v[28:31], v[148:151], v[210:213], v[28:31]
	v_mfma_f32_16x16x32_bf16 v[24:27], v[170:173], v[210:213], v[24:27]
	v_mfma_f32_16x16x32_bf16 v[24:27], v[160:163], v[206:209], v[24:27]
	v_mfma_f32_16x16x32_bf16 v[8:11], v[160:163], v[214:217], v[8:11]
	v_mfma_f32_16x16x32_bf16 v[8:11], v[170:173], v[218:221], v[8:11]
	v_mfma_f32_16x16x32_bf16 v[12:15], v[148:151], v[218:221], v[12:15]
	v_mfma_f32_16x16x32_bf16 v[12:15], v[144:147], v[214:217], v[12:15]
	s_setprio 0
	s_setprio 1
	v_mfma_f32_16x16x32_bf16 v[52:55], v[174:177], v[190:193], v[52:55]
	v_mfma_f32_16x16x32_bf16 v[52:55], v[178:181], v[194:197], v[52:55]
	v_mfma_f32_16x16x32_bf16 v[48:51], v[186:189], v[194:197], v[48:51]
	v_mfma_f32_16x16x32_bf16 v[48:51], v[182:185], v[190:193], v[48:51]
	v_mfma_f32_16x16x32_bf16 v[32:35], v[182:185], v[198:201], v[32:35]
	v_mfma_f32_16x16x32_bf16 v[32:35], v[186:189], v[202:205], v[32:35]
	v_mfma_f32_16x16x32_bf16 v[36:39], v[178:181], v[202:205], v[36:39]
	v_mfma_f32_16x16x32_bf16 v[36:39], v[174:177], v[198:201], v[36:39]
	v_mfma_f32_16x16x32_bf16 v[20:23], v[174:177], v[206:209], v[20:23]
	v_mfma_f32_16x16x32_bf16 v[20:23], v[178:181], v[210:213], v[20:23]
	v_mfma_f32_16x16x32_bf16 v[16:19], v[186:189], v[210:213], v[16:19]
	v_mfma_f32_16x16x32_bf16 v[16:19], v[182:185], v[206:209], v[16:19]
	v_mfma_f32_16x16x32_bf16 v[0:3], v[182:185], v[214:217], v[0:3]
	v_mfma_f32_16x16x32_bf16 v[0:3], v[186:189], v[218:221], v[0:3]
	v_mfma_f32_16x16x32_bf16 v[4:7], v[178:181], v[218:221], v[4:7]
	v_mfma_f32_16x16x32_bf16 v[4:7], v[174:177], v[214:217], v[4:7]
	s_setprio 0
	s_barrier
; #define PG8_STAGE(bufoff, gbase, voff) do { _Pragma("unroll") for (int _i = 0; _i < 2; ++_i) \
;         __builtin_amdgcn_global_load_lds((const unsigned*)((const char*)(gbase) + (voff)[_i]), (LAS unsigned*)(lds + (bufoff) + ldsw + _i * 8192), 16, 0, 0); } while (0)
; #define PG8_LDA(dst, b, h) do { _Pragma("unroll") for (int m = 0; m < 4; ++m) _Pragma("unroll") for (int k = 0; k < 2; ++k) dst[m][k] = *(const LAS bf16x8*)(lds + PG8_SA(b, h) + aoff + m * 2048 + k * 1024); } while (0)
; #define PG8_LDB(dst, b, h) do { _Pragma("unroll") for (int n = 0; n < 2; ++n) _Pragma("unroll") for (int k = 0; k < 2; ++k) dst[n][k] = *(const LAS bf16x8*)(lds + PG8_SB(b, h) + boff + n * 2048 + k * 1024); } while (0)
; #define PG8_MMA(ai, bj, At, Bt) do { __builtin_amdgcn_s_setprio(1); _Pragma("unroll") for (int m = 0; m < 4; ++m) _Pragma("unroll") for (int n = 0; n < 2; ++n) _Pragma("unroll") for (int k = 0; k < 2; ++k) \
;         acc[ai][bj][m][n] = __builtin_amdgcn_mfma_f32_16x16x32_bf16(Bt[n][k], At[m][k], acc[ai][bj][m][n], 0, 0, 0); __builtin_amdgcn_s_setprio(0); } while (0)
; #define PG8_WAIT_V(n) asm volatile("s_waitcnt vmcnt(" #n ")" ::: "memory")
; #define PG8_WAIT_L(n) asm volatile("s_waitcnt lgkmcnt(" #n ")" ::: "memory")
; #define PG8_BAR __builtin_amdgcn_s_barrier()
; #define PG8_SCHED __builtin_amdgcn_sched_barrier(0)
; DI void gemm_phase(LAS unsigned char* lds, const Gemm g, const StaticOrder& S, const Epi& E) {
;     ...
;             PG8_LDB(B0, 1, 0); PG8_LDB(B1, 1, 1); PG8_SCHED; PG8_LDA(At, 1, 0); PG8_STAGE(PG8_SA(0, 1), a2 + hsA, voffA);
;             PG8_WAIT_V(8); PG8_WAIT_L(0); PG8_BAR; PG8_MMA(0, 0, At, B0); PG8_MMA(0, 1, At, B1); PG8_BAR; PG8_SCHED;
;             PG8_LDA(At, 1, 1); PG8_STAGE(PG8_SB(1, 0), b3, voffB); PG8_STAGE(PG8_SB(1, 1), b3 + hsB, voffB); PG8_STAGE(PG8_SA(1, 0), a3, voffA);
;             PG8_WAIT_V(8); PG8_WAIT_L(0); PG8_BAR; PG8_MMA(1, 0, At, B0); PG8_MMA(1, 1, At, B1); PG8_BAR; PG8_SCHED;
;         }
;         if (wr == 0) PG8_BAR;
	s_add_i32 s46, 0, 0x18000
	v_add_u32_e32 v159, s46, v153
	s_add_i32 s47, 0, 0x1c000
	ds_read_b128 v[144:147], v159
	ds_read_b128 v[148:151], v159 offset:1024
	ds_read_b128 v[160:163], v159 offset:2048
	ds_read_b128 v[170:173], v159 offset:3072
	v_add_u32_e32 v159, s47, v153
	ds_read_b128 v[174:177], v159
	ds_read_b128 v[178:181], v159 offset:1024
	ds_read_b128 v[182:185], v159 offset:2048
	ds_read_b128 v[186:189], v159 offset:3072
	s_add_u32 s28, s28, 0x80000
	s_addc_u32 s29, s29, 0
	s_mov_b32 m0, s31
	ds_read_b128 v[190:193], v157 offset:32768
	ds_read_b128 v[194:197], v157 offset:33792
	ds_read_b128 v[198:201], v157 offset:34816
	ds_read_b128 v[202:205], v157 offset:35840
	ds_read_b128 v[206:209], v157 offset:36864
	ds_read_b128 v[210:213], v157 offset:37888
	ds_read_b128 v[214:217], v157 offset:38912
	ds_read_b128 v[218:221], v157 offset:39936
	global_load_lds_dwordx4 v134, s[28:29]
	s_mov_b32 m0, s33
	s_nop 0
	global_load_lds_dwordx4 v130, s[28:29]
	s_waitcnt vmcnt(8)
	s_waitcnt lgkmcnt(0)
	s_barrier
	s_setprio 1
	s_waitcnt lgkmcnt(0)
	v_mfma_f32_16x16x32_bf16 v[124:127], v[144:147], v[190:193], v[124:127]
	v_mfma_f32_16x16x32_bf16 v[124:127], v[148:151], v[194:197], v[124:127]
	v_mfma_f32_16x16x32_bf16 v[120:123], v[170:173], v[194:197], v[120:123]
	v_mfma_f32_16x16x32_bf16 v[120:123], v[160:163], v[190:193], v[120:123]
	v_mfma_f32_16x16x32_bf16 v[104:107], v[160:163], v[198:201], v[104:107]
	v_mfma_f32_16x16x32_bf16 v[104:107], v[170:173], v[202:205], v[104:107]
	v_mfma_f32_16x16x32_bf16 v[108:111], v[148:151], v[202:205], v[108:111]
	v_mfma_f32_16x16x32_bf16 v[108:111], v[144:147], v[198:201], v[108:111]
	v_mfma_f32_16x16x32_bf16 v[92:95], v[144:147], v[206:209], v[92:95]
	v_mfma_f32_16x16x32_bf16 v[92:95], v[148:151], v[210:213], v[92:95]
	v_mfma_f32_16x16x32_bf16 v[88:91], v[170:173], v[210:213], v[88:91]
	v_mfma_f32_16x16x32_bf16 v[88:91], v[160:163], v[206:209], v[88:91]
	v_mfma_f32_16x16x32_bf16 v[72:75], v[160:163], v[214:217], v[72:75]
	v_mfma_f32_16x16x32_bf16 v[72:75], v[170:173], v[218:221], v[72:75]
	v_mfma_f32_16x16x32_bf16 v[76:79], v[148:151], v[218:221], v[76:79]
	v_mfma_f32_16x16x32_bf16 v[76:79], v[144:147], v[214:217], v[76:79]
	s_setprio 0
	s_setprio 1
	v_mfma_f32_16x16x32_bf16 v[116:119], v[174:177], v[190:193], v[116:119]
	v_mfma_f32_16x16x32_bf16 v[116:119], v[178:181], v[194:197], v[116:119]
	v_mfma_f32_16x16x32_bf16 v[112:115], v[186:189], v[194:197], v[112:115]
	v_mfma_f32_16x16x32_bf16 v[112:115], v[182:185], v[190:193], v[112:115]
	v_mfma_f32_16x16x32_bf16 v[96:99], v[182:185], v[198:201], v[96:99]
	v_mfma_f32_16x16x32_bf16 v[96:99], v[186:189], v[202:205], v[96:99]
	v_mfma_f32_16x16x32_bf16 v[100:103], v[178:181], v[202:205], v[100:103]
	v_mfma_f32_16x16x32_bf16 v[100:103], v[174:177], v[198:201], v[100:103]
	v_mfma_f32_16x16x32_bf16 v[84:87], v[174:177], v[206:209], v[84:87]
	v_mfma_f32_16x16x32_bf16 v[84:87], v[178:181], v[210:213], v[84:87]
	v_mfma_f32_16x16x32_bf16 v[80:83], v[186:189], v[210:213], v[80:83]
	v_mfma_f32_16x16x32_bf16 v[80:83], v[182:185], v[206:209], v[80:83]
	v_mfma_f32_16x16x32_bf16 v[64:67], v[182:185], v[214:217], v[64:67]
	v_mfma_f32_16x16x32_bf16 v[64:67], v[186:189], v[218:221], v[64:67]
	v_mfma_f32_16x16x32_bf16 v[68:71], v[178:181], v[218:221], v[68:71]
	v_mfma_f32_16x16x32_bf16 v[68:71], v[174:177], v[214:217], v[68:71]
	s_setprio 0
	s_barrier
	s_add_i32 s28, s46, s12
	s_mov_b32 m0, s28
	ds_read_b128 v[190:193], v157 offset:49152
	ds_read_b128 v[194:197], v157 offset:50176
	ds_read_b128 v[198:201], v157 offset:51200
	ds_read_b128 v[202:205], v157 offset:52224
	ds_read_b128 v[206:209], v157 offset:53248
	ds_read_b128 v[210:213], v157 offset:54272
	ds_read_b128 v[214:217], v157 offset:55296
	ds_read_b128 v[218:221], v157 offset:56320
	global_load_lds_dwordx4 v132, s[98:99]
	s_add_i32 m0, s28, 0x2000
	s_add_u32 s26, s26, 0x80080
	s_addc_u32 s27, s27, 0
	s_add_i32 s28, s47, s12
	global_load_lds_dwordx4 v128, s[98:99]
	s_mov_b32 m0, s28
	s_nop 0
	global_load_lds_dwordx4 v132, s[26:27]
	s_add_i32 m0, s28, 0x2000
	s_nop 0
	global_load_lds_dwordx4 v128, s[26:27]
	s_mov_b32 m0, s35
	s_nop 0
	global_load_lds_dwordx4 v134, s[100:101]
	s_mov_b32 m0, s36
	s_nop 0
	global_load_lds_dwordx4 v130, s[100:101]
	s_waitcnt vmcnt(8)
	s_waitcnt lgkmcnt(0)
	s_barrier
	s_setprio 1
	s_waitcnt lgkmcnt(0)
	v_mfma_f32_16x16x32_bf16 v[60:63], v[144:147], v[190:193], v[60:63]
	v_mfma_f32_16x16x32_bf16 v[60:63], v[148:151], v[194:197], v[60:63]
	v_mfma_f32_16x16x32_bf16 v[56:59], v[170:173], v[194:197], v[56:59]
	v_mfma_f32_16x16x32_bf16 v[56:59], v[160:163], v[190:193], v[56:59]
	v_mfma_f32_16x16x32_bf16 v[40:43], v[160:163], v[198:201], v[40:43]
	v_mfma_f32_16x16x32_bf16 v[40:43], v[170:173], v[202:205], v[40:43]
	v_mfma_f32_16x16x32_bf16 v[44:47], v[148:151], v[202:205], v[44:47]
	v_mfma_f32_16x16x32_bf16 v[44:47], v[144:147], v[198:201], v[44:47]
	v_mfma_f32_16x16x32_bf16 v[28:31], v[144:147], v[206:209], v[28:31]
	v_mfma_f32_16x16x32_bf16 v[28:31], v[148:151], v[210:213], v[28:31]
	v_mfma_f32_16x16x32_bf16 v[24:27], v[170:173], v[210:213], v[24:27]
	v_mfma_f32_16x16x32_bf16 v[24:27], v[160:163], v[206:209], v[24:27]
	v_mfma_f32_16x16x32_bf16 v[8:11], v[160:163], v[214:217], v[8:11]
	v_mfma_f32_16x16x32_bf16 v[8:11], v[170:173], v[218:221], v[8:11]
	v_mfma_f32_16x16x32_bf16 v[12:15], v[148:151], v[218:221], v[12:15]
	v_mfma_f32_16x16x32_bf16 v[12:15], v[144:147], v[214:217], v[12:15]
	s_setprio 0
	s_setprio 1
	v_mfma_f32_16x16x32_bf16 v[52:55], v[174:177], v[190:193], v[52:55]
	v_mfma_f32_16x16x32_bf16 v[52:55], v[178:181], v[194:197], v[52:55]
	v_mfma_f32_16x16x32_bf16 v[48:51], v[186:189], v[194:197], v[48:51]
	v_mfma_f32_16x16x32_bf16 v[48:51], v[182:185], v[190:193], v[48:51]
	v_mfma_f32_16x16x32_bf16 v[32:35], v[182:185], v[198:201], v[32:35]
	v_mfma_f32_16x16x32_bf16 v[32:35], v[186:189], v[202:205], v[32:35]
	v_mfma_f32_16x16x32_bf16 v[36:39], v[178:181], v[202:205], v[36:39]
	v_mfma_f32_16x16x32_bf16 v[36:39], v[174:177], v[198:201], v[36:39]
	v_mfma_f32_16x16x32_bf16 v[20:23], v[174:177], v[206:209], v[20:23]
	v_mfma_f32_16x16x32_bf16 v[20:23], v[178:181], v[210:213], v[20:23]
	v_mfma_f32_16x16x32_bf16 v[16:19], v[186:189], v[210:213], v[16:19]
	v_mfma_f32_16x16x32_bf16 v[16:19], v[182:185], v[206:209], v[16:19]
	v_mfma_f32_16x16x32_bf16 v[0:3], v[182:185], v[214:217], v[0:3]
	v_mfma_f32_16x16x32_bf16 v[0:3], v[186:189], v[218:221], v[0:3]
	v_mfma_f32_16x16x32_bf16 v[4:7], v[178:181], v[218:221], v[4:7]
	v_mfma_f32_16x16x32_bf16 v[4:7], v[174:177], v[214:217], v[4:7]
	s_setprio 0
	s_barrier
	s_add_i32 s49, s49, 2
	s_add_u32 s24, s24, 0x100
	s_addc_u32 s25, s25, 0
	s_add_u32 s43, s43, 0x100
	s_addc_u32 s48, s48, 0
	s_cmp_gt_u32 s49, 29
	s_cbranch_scc0 .LBB0_1020
	s_and_b64 vcc, exec, s[10:11]
	s_cbranch_vccz .LBB0_1023
	s_barrier

; #define PG8_STAGE(bufoff, gbase, voff) do { _Pragma("unroll") for (int _i = 0; _i < 2; ++_i) \
;         __builtin_amdgcn_global_load_lds((const unsigned*)((const char*)(gbase) + (voff)[_i]), (LAS unsigned*)(lds + (bufoff) + ldsw + _i * 8192), 16, 0, 0); } while (0)
; #define PG8_LDA(dst, b, h) do { _Pragma("unroll") for (int m = 0; m < 4; ++m) _Pragma("unroll") for (int k = 0; k < 2; ++k) dst[m][k] = *(const LAS bf16x8*)(lds + PG8_SA(b, h) + aoff + m * 2048 + k * 1024); } while (0)
; #define PG8_LDB(dst, b, h) do { _Pragma("unroll") for (int n = 0; n < 2; ++n) _Pragma("unroll") for (int k = 0; k < 2; ++k) dst[n][k] = *(const LAS bf16x8*)(lds + PG8_SB(b, h) + boff + n * 2048 + k * 1024); } while (0)
; #define PG8_MMA(ai, bj, At, Bt) do { __builtin_amdgcn_s_setprio(1); _Pragma("unroll") for (int m = 0; m < 4; ++m) _Pragma("unroll") for (int n = 0; n < 2; ++n) _Pragma("unroll") for (int k = 0; k < 2; ++k) \
;         acc[ai][bj][m][n] = __builtin_amdgcn_mfma_f32_16x16x32_bf16(Bt[n][k], At[m][k], acc[ai][bj][m][n], 0, 0, 0); __builtin_amdgcn_s_setprio(0); } while (0)
; #define PG8_WAIT_V(n) asm volatile("s_waitcnt vmcnt(" #n ")" ::: "memory")
; #define PG8_WAIT_L(n) asm volatile("s_waitcnt lgkmcnt(" #n ")" ::: "memory")
; #define PG8_BAR __builtin_amdgcn_s_barrier()
; #define PG8_SCHED __builtin_amdgcn_sched_barrier(0)
; DI void gemm_phase(LAS unsigned char* lds, const Gemm g, const StaticOrder& S, const Epi& E) {
;     ...
;             PG8_LDB(B0, 0, 0); PG8_LDB(B1, 0, 1); PG8_SCHED; PG8_LDA(At, 0, 0); PG8_STAGE(PG8_SA(1, 1), a1 + hsA, voffA);
;             PG8_WAIT_V(8); PG8_WAIT_L(0); PG8_BAR; PG8_MMA(0, 0, At, B0); PG8_MMA(0, 1, At, B1); PG8_BAR; PG8_SCHED;
;             PG8_LDA(At, 0, 1); PG8_STAGE(PG8_SB(0, 0), b2, voffB); PG8_STAGE(PG8_SB(0, 1), b2 + hsB, voffB); PG8_STAGE(PG8_SA(0, 0), a2, voffA);
;             PG8_WAIT_V(8); PG8_WAIT_L(0); PG8_BAR; PG8_MMA(1, 0, At, B0); PG8_MMA(1, 1, At, B1); PG8_BAR; PG8_SCHED;
.LBB0_1101:
	ds_read_b128 v[128:131], v165
	ds_read_b128 v[132:135], v165 offset:1024
	ds_read_b128 v[136:139], v165 offset:2048
	ds_read_b128 v[156:159], v165 offset:3072
	ds_read_b128 v[170:173], v166
	ds_read_b128 v[174:177], v166 offset:1024
	ds_read_b128 v[178:181], v166 offset:2048
	ds_read_b128 v[182:185], v166 offset:3072
	s_add_u32 s26, s24, 0x100
	s_addc_u32 s27, s25, 0
	s_cmpk_eq_i32 s53, 0x54
	s_cselect_b32 s31, s5, s27
	s_cselect_b32 s30, s4, s26
	s_cselect_b32 s29, s23, s52
	s_cselect_b32 s28, s22, s51
	s_add_i32 m0, s13, 0xc000
	ds_read_b128 v[186:189], v168
	ds_read_b128 v[190:193], v168 offset:1024
	ds_read_b128 v[194:197], v168 offset:2048
	ds_read_b128 v[198:201], v168 offset:3072
	ds_read_b128 v[202:205], v168 offset:4096
	ds_read_b128 v[206:209], v168 offset:5120
	ds_read_b128 v[210:213], v168 offset:6144
	ds_read_b128 v[214:217], v168 offset:7168
	global_load_lds_dwordx4 v148, s[24:25]
	s_add_i32 m0, s13, 0xe000
	s_nop 0
	global_load_lds_dwordx4 v150, s[24:25]
	s_waitcnt vmcnt(8)
	s_waitcnt lgkmcnt(0)
	s_barrier
	s_setprio 1
	s_waitcnt lgkmcnt(0)
	v_mfma_f32_16x16x32_bf16 v[124:127], v[128:131], v[186:189], v[124:127]
	v_mfma_f32_16x16x32_bf16 v[124:127], v[132:135], v[190:193], v[124:127]
	v_mfma_f32_16x16x32_bf16 v[120:123], v[156:159], v[190:193], v[120:123]
	v_mfma_f32_16x16x32_bf16 v[120:123], v[136:139], v[186:189], v[120:123]
	v_mfma_f32_16x16x32_bf16 v[104:107], v[136:139], v[194:197], v[104:107]
	v_mfma_f32_16x16x32_bf16 v[104:107], v[156:159], v[198:201], v[104:107]
	v_mfma_f32_16x16x32_bf16 v[112:115], v[132:135], v[198:201], v[112:115]
	v_mfma_f32_16x16x32_bf16 v[112:115], v[128:131], v[194:197], v[112:115]
	v_mfma_f32_16x16x32_bf16 v[92:95], v[128:131], v[202:205], v[92:95]
	v_mfma_f32_16x16x32_bf16 v[92:95], v[132:135], v[206:209], v[92:95]
	v_mfma_f32_16x16x32_bf16 v[88:91], v[156:159], v[206:209], v[88:91]
	v_mfma_f32_16x16x32_bf16 v[88:91], v[136:139], v[202:205], v[88:91]
	v_mfma_f32_16x16x32_bf16 v[72:75], v[136:139], v[210:213], v[72:75]
	v_mfma_f32_16x16x32_bf16 v[72:75], v[156:159], v[214:217], v[72:75]
	v_mfma_f32_16x16x32_bf16 v[76:79], v[132:135], v[214:217], v[76:79]
	v_mfma_f32_16x16x32_bf16 v[76:79], v[128:131], v[210:213], v[76:79]
	s_setprio 0
	s_setprio 1
	v_mfma_f32_16x16x32_bf16 v[116:119], v[170:173], v[186:189], v[116:119]
	v_mfma_f32_16x16x32_bf16 v[116:119], v[174:177], v[190:193], v[116:119]
	v_mfma_f32_16x16x32_bf16 v[108:111], v[182:185], v[190:193], v[108:111]
	v_mfma_f32_16x16x32_bf16 v[108:111], v[178:181], v[186:189], v[108:111]
	v_mfma_f32_16x16x32_bf16 v[96:99], v[178:181], v[194:197], v[96:99]
	v_mfma_f32_16x16x32_bf16 v[96:99], v[182:185], v[198:201], v[96:99]
	v_mfma_f32_16x16x32_bf16 v[100:103], v[174:177], v[198:201], v[100:103]
	v_mfma_f32_16x16x32_bf16 v[100:103], v[170:173], v[194:197], v[100:103]
	v_mfma_f32_16x16x32_bf16 v[84:87], v[170:173], v[202:205], v[84:87]
	v_mfma_f32_16x16x32_bf16 v[84:87], v[174:177], v[206:209], v[84:87]
	v_mfma_f32_16x16x32_bf16 v[80:83], v[182:185], v[206:209], v[80:83]
	v_mfma_f32_16x16x32_bf16 v[80:83], v[178:181], v[202:205], v[80:83]
	v_mfma_f32_16x16x32_bf16 v[64:67], v[178:181], v[210:213], v[64:67]
	v_mfma_f32_16x16x32_bf16 v[64:67], v[182:185], v[214:217], v[64:67]
	v_mfma_f32_16x16x32_bf16 v[68:71], v[174:177], v[214:217], v[68:71]
	v_mfma_f32_16x16x32_bf16 v[68:71], v[170:173], v[210:213], v[68:71]
	s_setprio 0
	s_barrier
	s_add_i32 s24, s39, s12
	s_add_u32 s98, s28, 0x80
	s_addc_u32 s99, s29, 0
	s_mov_b32 m0, s24
	ds_read_b128 v[186:189], v168 offset:16384
	ds_read_b128 v[190:193], v168 offset:17408
	ds_read_b128 v[194:197], v168 offset:18432
	ds_read_b128 v[198:201], v168 offset:19456
	ds_read_b128 v[202:205], v168 offset:20480
	ds_read_b128 v[206:209], v168 offset:21504
	ds_read_b128 v[210:213], v168 offset:22528
	ds_read_b128 v[214:217], v168 offset:23552
	global_load_lds_dwordx4 v142, s[28:29]
	s_add_i32 m0, s24, 0x2000
	s_add_u32 s24, s28, 0x160000
	s_addc_u32 s25, s29, 0
	s_add_i32 s54, s40, s12
	global_load_lds_dwordx4 v146, s[28:29]
	s_mov_b32 m0, s54
	s_nop 0
	global_load_lds_dwordx4 v142, s[24:25]
	s_add_i32 m0, s54, 0x2000
	s_nop 0
	global_load_lds_dwordx4 v146, s[24:25]
	s_add_u32 s100, s30, 0x80
	s_addc_u32 s101, s31, 0
	s_mov_b32 m0, s13
	s_nop 0
	global_load_lds_dwordx4 v140, s[30:31]
	s_mov_b32 m0, s33
	s_nop 0
	global_load_lds_dwordx4 v144, s[30:31]
	s_waitcnt vmcnt(8)
	s_waitcnt lgkmcnt(0)
	s_barrier
	s_setprio 1
	s_waitcnt lgkmcnt(0)
	v_mfma_f32_16x16x32_bf16 v[60:63], v[128:131], v[186:189], v[60:63]
	v_mfma_f32_16x16x32_bf16 v[60:63], v[132:135], v[190:193], v[60:63]
	v_mfma_f32_16x16x32_bf16 v[56:59], v[156:159], v[190:193], v[56:59]
	v_mfma_f32_16x16x32_bf16 v[56:59], v[136:139], v[186:189], v[56:59]
	v_mfma_f32_16x16x32_bf16 v[40:43], v[136:139], v[194:197], v[40:43]
	v_mfma_f32_16x16x32_bf16 v[40:43], v[156:159], v[198:201], v[40:43]
	v_mfma_f32_16x16x32_bf16 v[48:51], v[132:135], v[198:201], v[48:51]
	v_mfma_f32_16x16x32_bf16 v[48:51], v[128:131], v[194:197], v[48:51]
	v_mfma_f32_16x16x32_bf16 v[36:39], v[128:131], v[202:205], v[36:39]
	v_mfma_f32_16x16x32_bf16 v[36:39], v[132:135], v[206:209], v[36:39]
	v_mfma_f32_16x16x32_bf16 v[28:31], v[156:159], v[206:209], v[28:31]
	v_mfma_f32_16x16x32_bf16 v[28:31], v[136:139], v[202:205], v[28:31]
	v_mfma_f32_16x16x32_bf16 v[12:15], v[136:139], v[210:213], v[12:15]
	v_mfma_f32_16x16x32_bf16 v[12:15], v[156:159], v[214:217], v[12:15]
	v_mfma_f32_16x16x32_bf16 v[20:23], v[132:135], v[214:217], v[20:23]
	v_mfma_f32_16x16x32_bf16 v[20:23], v[128:131], v[210:213], v[20:23]
	s_setprio 0
	s_setprio 1
	v_mfma_f32_16x16x32_bf16 v[52:55], v[170:173], v[186:189], v[52:55]
	v_mfma_f32_16x16x32_bf16 v[52:55], v[174:177], v[190:193], v[52:55]
	v_mfma_f32_16x16x32_bf16 v[44:47], v[182:185], v[190:193], v[44:47]
	v_mfma_f32_16x16x32_bf16 v[44:47], v[178:181], v[186:189], v[44:47]
	v_mfma_f32_16x16x32_bf16 v[24:27], v[178:181], v[194:197], v[24:27]
	v_mfma_f32_16x16x32_bf16 v[24:27], v[182:185], v[198:201], v[24:27]
	v_mfma_f32_16x16x32_bf16 v[32:35], v[174:177], v[198:201], v[32:35]
	v_mfma_f32_16x16x32_bf16 v[32:35], v[170:173], v[194:197], v[32:35]
	v_mfma_f32_16x16x32_bf16 v[16:19], v[170:173], v[202:205], v[16:19]
	v_mfma_f32_16x16x32_bf16 v[16:19], v[174:177], v[206:209], v[16:19]
	v_mfma_f32_16x16x32_bf16 v[8:11], v[182:185], v[206:209], v[8:11]
	v_mfma_f32_16x16x32_bf16 v[8:11], v[178:181], v[202:205], v[8:11]
	v_mfma_f32_16x16x32_bf16 v[0:3], v[178:181], v[210:213], v[0:3]
	v_mfma_f32_16x16x32_bf16 v[0:3], v[182:185], v[214:217], v[0:3]
	v_mfma_f32_16x16x32_bf16 v[4:7], v[174:177], v[214:217], v[4:7]
	v_mfma_f32_16x16x32_bf16 v[4:7], v[170:173], v[210:213], v[4:7]
	s_setprio 0
	s_barrier
; #define PG8_STAGE(bufoff, gbase, voff) do { _Pragma("unroll") for (int _i = 0; _i < 2; ++_i) \
;         __builtin_amdgcn_global_load_lds((const unsigned*)((const char*)(gbase) + (voff)[_i]), (LAS unsigned*)(lds + (bufoff) + ldsw + _i * 8192), 16, 0, 0); } while (0)
; #define PG8_LDA(dst, b, h) do { _Pragma("unroll") for (int m = 0; m < 4; ++m) _Pragma("unroll") for (int k = 0; k < 2; ++k) dst[m][k] = *(const LAS bf16x8*)(lds + PG8_SA(b, h) + aoff + m * 2048 + k * 1024); } while (0)
; #define PG8_LDB(dst, b, h) do { _Pragma("unroll") for (int n = 0; n < 2; ++n) _Pragma("unroll") for (int k = 0; k < 2; ++k) dst[n][k] = *(const LAS bf16x8*)(lds + PG8_SB(b, h) + boff + n * 2048 + k * 1024); } while (0)
; #define PG8_MMA(ai, bj, At, Bt) do { __builtin_amdgcn_s_setprio(1); _Pragma("unroll") for (int m = 0; m < 4; ++m) _Pragma("unroll") for (int n = 0; n < 2; ++n) _Pragma("unroll") for (int k = 0; k < 2; ++k) \
;         acc[ai][bj][m][n] = __builtin_amdgcn_mfma_f32_16x16x32_bf16(Bt[n][k], At[m][k], acc[ai][bj][m][n], 0, 0, 0); __builtin_amdgcn_s_setprio(0); } while (0)
; #define PG8_WAIT_V(n) asm volatile("s_waitcnt vmcnt(" #n ")" ::: "memory")
; #define PG8_WAIT_L(n) asm volatile("s_waitcnt lgkmcnt(" #n ")" ::: "memory")
; #define PG8_BAR __builtin_amdgcn_s_barrier()
; #define PG8_SCHED __builtin_amdgcn_sched_barrier(0)
; DI void gemm_phase(LAS unsigned char* lds, const Gemm g, const StaticOrder& S, const Epi& E) {
;     ...
;             PG8_LDB(B0, 1, 0); PG8_LDB(B1, 1, 1); PG8_SCHED; PG8_LDA(At, 1, 0); PG8_STAGE(PG8_SA(0, 1), a2 + hsA, voffA);
;             PG8_WAIT_V(8); PG8_WAIT_L(0); PG8_BAR; PG8_MMA(0, 0, At, B0); PG8_MMA(0, 1, At, B1); PG8_BAR; PG8_SCHED;
;             PG8_LDA(At, 1, 1); PG8_STAGE(PG8_SB(1, 0), b3, voffB); PG8_STAGE(PG8_SB(1, 1), b3 + hsB, voffB); PG8_STAGE(PG8_SA(1, 0), a3, voffA);
;             PG8_WAIT_V(8); PG8_WAIT_L(0); PG8_BAR; PG8_MMA(1, 0, At, B0); PG8_MMA(1, 1, At, B1); PG8_BAR; PG8_SCHED;
;         }
	s_add_i32 s54, 0, 0x18000
	s_add_i32 s55, 0, 0x1c000
	v_add_u32_e32 v156, s54, v163
	v_add_u32_e32 v182, s55, v163
	ds_read_b128 v[128:131], v156
	ds_read_b128 v[132:135], v156 offset:1024
	ds_read_b128 v[136:139], v156 offset:2048
	ds_read_b128 v[156:159], v156 offset:3072
	ds_read_b128 v[170:173], v182
	ds_read_b128 v[174:177], v182 offset:1024
	ds_read_b128 v[178:181], v182 offset:2048
	ds_read_b128 v[182:185], v182 offset:3072
	s_add_u32 s24, s30, 0x160000
	s_addc_u32 s25, s31, 0
	s_mov_b32 m0, s34
	ds_read_b128 v[186:189], v168 offset:32768
	ds_read_b128 v[190:193], v168 offset:33792
	ds_read_b128 v[194:197], v168 offset:34816
	ds_read_b128 v[198:201], v168 offset:35840
	ds_read_b128 v[202:205], v168 offset:36864
	ds_read_b128 v[206:209], v168 offset:37888
	ds_read_b128 v[210:213], v168 offset:38912
	ds_read_b128 v[214:217], v168 offset:39936
	global_load_lds_dwordx4 v140, s[24:25]
	s_mov_b32 m0, s35
	s_nop 0
	global_load_lds_dwordx4 v144, s[24:25]
	s_waitcnt vmcnt(8)
	s_waitcnt lgkmcnt(0)
	s_barrier
	s_setprio 1
	s_waitcnt lgkmcnt(0)
	v_mfma_f32_16x16x32_bf16 v[124:127], v[128:131], v[186:189], v[124:127]
	v_mfma_f32_16x16x32_bf16 v[124:127], v[132:135], v[190:193], v[124:127]
	v_mfma_f32_16x16x32_bf16 v[120:123], v[156:159], v[190:193], v[120:123]
	v_mfma_f32_16x16x32_bf16 v[120:123], v[136:139], v[186:189], v[120:123]
	v_mfma_f32_16x16x32_bf16 v[104:107], v[136:139], v[194:197], v[104:107]
	v_mfma_f32_16x16x32_bf16 v[104:107], v[156:159], v[198:201], v[104:107]
	v_mfma_f32_16x16x32_bf16 v[112:115], v[132:135], v[198:201], v[112:115]
	v_mfma_f32_16x16x32_bf16 v[112:115], v[128:131], v[194:197], v[112:115]
	v_mfma_f32_16x16x32_bf16 v[92:95], v[128:131], v[202:205], v[92:95]
	v_mfma_f32_16x16x32_bf16 v[92:95], v[132:135], v[206:209], v[92:95]
	v_mfma_f32_16x16x32_bf16 v[88:91], v[156:159], v[206:209], v[88:91]
	v_mfma_f32_16x16x32_bf16 v[88:91], v[136:139], v[202:205], v[88:91]
	v_mfma_f32_16x16x32_bf16 v[72:75], v[136:139], v[210:213], v[72:75]
	v_mfma_f32_16x16x32_bf16 v[72:75], v[156:159], v[214:217], v[72:75]
	v_mfma_f32_16x16x32_bf16 v[76:79], v[132:135], v[214:217], v[76:79]
	v_mfma_f32_16x16x32_bf16 v[76:79], v[128:131], v[210:213], v[76:79]
	s_setprio 0
	s_setprio 1
	v_mfma_f32_16x16x32_bf16 v[116:119], v[170:173], v[186:189], v[116:119]
	v_mfma_f32_16x16x32_bf16 v[116:119], v[174:177], v[190:193], v[116:119]
	v_mfma_f32_16x16x32_bf16 v[108:111], v[182:185], v[190:193], v[108:111]
	v_mfma_f32_16x16x32_bf16 v[108:111], v[178:181], v[186:189], v[108:111]
	v_mfma_f32_16x16x32_bf16 v[96:99], v[178:181], v[194:197], v[96:99]
	v_mfma_f32_16x16x32_bf16 v[96:99], v[182:185], v[198:201], v[96:99]
	v_mfma_f32_16x16x32_bf16 v[100:103], v[174:177], v[198:201], v[100:103]
	v_mfma_f32_16x16x32_bf16 v[100:103], v[170:173], v[194:197], v[100:103]
	v_mfma_f32_16x16x32_bf16 v[84:87], v[170:173], v[202:205], v[84:87]
	v_mfma_f32_16x16x32_bf16 v[84:87], v[174:177], v[206:209], v[84:87]
	v_mfma_f32_16x16x32_bf16 v[80:83], v[182:185], v[206:209], v[80:83]
	v_mfma_f32_16x16x32_bf16 v[80:83], v[178:181], v[202:205], v[80:83]
	v_mfma_f32_16x16x32_bf16 v[64:67], v[178:181], v[210:213], v[64:67]
	v_mfma_f32_16x16x32_bf16 v[64:67], v[182:185], v[214:217], v[64:67]
	v_mfma_f32_16x16x32_bf16 v[68:71], v[174:177], v[214:217], v[68:71]
	v_mfma_f32_16x16x32_bf16 v[68:71], v[170:173], v[210:213], v[68:71]
	s_setprio 0
	s_barrier
	s_add_i32 s24, s54, s12
	s_mov_b32 m0, s24
	ds_read_b128 v[186:189], v168 offset:49152
	ds_read_b128 v[190:193], v168 offset:50176
	ds_read_b128 v[194:197], v168 offset:51200
	ds_read_b128 v[198:201], v168 offset:52224
	ds_read_b128 v[202:205], v168 offset:53248
	ds_read_b128 v[206:209], v168 offset:54272
	ds_read_b128 v[210:213], v168 offset:55296
	ds_read_b128 v[214:217], v168 offset:56320
	global_load_lds_dwordx4 v142, s[98:99]
	s_add_i32 m0, s24, 0x2000
	s_add_u32 s24, s28, 0x160080
	s_addc_u32 s25, s29, 0
	s_add_i32 s28, s55, s12
	global_load_lds_dwordx4 v146, s[98:99]
	s_mov_b32 m0, s28
	s_nop 0
	global_load_lds_dwordx4 v142, s[24:25]
	s_add_i32 m0, s28, 0x2000
	s_nop 0
	global_load_lds_dwordx4 v146, s[24:25]
	s_mov_b32 m0, s37
	s_nop 0
	global_load_lds_dwordx4 v140, s[100:101]
	s_mov_b32 m0, s38
	s_nop 0
	global_load_lds_dwordx4 v144, s[100:101]
	s_waitcnt vmcnt(8)
	s_waitcnt lgkmcnt(0)
	s_barrier
	s_setprio 1
	s_waitcnt lgkmcnt(0)
	v_mfma_f32_16x16x32_bf16 v[60:63], v[128:131], v[186:189], v[60:63]
	v_mfma_f32_16x16x32_bf16 v[60:63], v[132:135], v[190:193], v[60:63]
	v_mfma_f32_16x16x32_bf16 v[56:59], v[156:159], v[190:193], v[56:59]
	v_mfma_f32_16x16x32_bf16 v[56:59], v[136:139], v[186:189], v[56:59]
	v_mfma_f32_16x16x32_bf16 v[40:43], v[136:139], v[194:197], v[40:43]
	v_mfma_f32_16x16x32_bf16 v[40:43], v[156:159], v[198:201], v[40:43]
	v_mfma_f32_16x16x32_bf16 v[48:51], v[132:135], v[198:201], v[48:51]
	v_mfma_f32_16x16x32_bf16 v[48:51], v[128:131], v[194:197], v[48:51]
	v_mfma_f32_16x16x32_bf16 v[36:39], v[128:131], v[202:205], v[36:39]
	v_mfma_f32_16x16x32_bf16 v[36:39], v[132:135], v[206:209], v[36:39]
	v_mfma_f32_16x16x32_bf16 v[28:31], v[156:159], v[206:209], v[28:31]
	v_mfma_f32_16x16x32_bf16 v[28:31], v[136:139], v[202:205], v[28:31]
	v_mfma_f32_16x16x32_bf16 v[12:15], v[136:139], v[210:213], v[12:15]
	v_mfma_f32_16x16x32_bf16 v[12:15], v[156:159], v[214:217], v[12:15]
	v_mfma_f32_16x16x32_bf16 v[20:23], v[132:135], v[214:217], v[20:23]
	v_mfma_f32_16x16x32_bf16 v[20:23], v[128:131], v[210:213], v[20:23]
	s_setprio 0
	s_setprio 1
	v_mfma_f32_16x16x32_bf16 v[52:55], v[170:173], v[186:189], v[52:55]
	v_mfma_f32_16x16x32_bf16 v[52:55], v[174:177], v[190:193], v[52:55]
	v_mfma_f32_16x16x32_bf16 v[44:47], v[182:185], v[190:193], v[44:47]
	v_mfma_f32_16x16x32_bf16 v[44:47], v[178:181], v[186:189], v[44:47]
	v_mfma_f32_16x16x32_bf16 v[24:27], v[178:181], v[194:197], v[24:27]
	v_mfma_f32_16x16x32_bf16 v[24:27], v[182:185], v[198:201], v[24:27]
	v_mfma_f32_16x16x32_bf16 v[32:35], v[174:177], v[198:201], v[32:35]
	v_mfma_f32_16x16x32_bf16 v[32:35], v[170:173], v[194:197], v[32:35]
	v_mfma_f32_16x16x32_bf16 v[16:19], v[170:173], v[202:205], v[16:19]
	v_mfma_f32_16x16x32_bf16 v[16:19], v[174:177], v[206:209], v[16:19]
	v_mfma_f32_16x16x32_bf16 v[8:11], v[182:185], v[206:209], v[8:11]
	v_mfma_f32_16x16x32_bf16 v[8:11], v[178:181], v[202:205], v[8:11]
	v_mfma_f32_16x16x32_bf16 v[0:3], v[178:181], v[210:213], v[0:3]
	v_mfma_f32_16x16x32_bf16 v[0:3], v[182:185], v[214:217], v[0:3]
	v_mfma_f32_16x16x32_bf16 v[4:7], v[174:177], v[214:217], v[4:7]
	v_mfma_f32_16x16x32_bf16 v[4:7], v[170:173], v[210:213], v[4:7]
	s_setprio 0
	s_barrier
	s_add_i32 s53, s53, 2
	s_add_u32 s51, s51, 0x100
	s_addc_u32 s52, s52, 0
	s_cmpk_gt_u32 s53, 0x55
	s_mov_b64 s[24:25], s[26:27]
	s_cbranch_scc0 .LBB0_1101
	s_and_b64 vcc, exec, s[10:11]
	s_cbranch_vccz .LBB0_1104
	s_barrier

; __global__ void __launch_bounds__(NTHREADS, 2) fwd_megakernel(Params p) {
;     extern __shared__ __attribute__((aligned(16))) unsigned char dyn_lds[];
	.amdhsa_kernel _Z14fwd_megakernel6Params
		.amdhsa_group_segment_fixed_size 0
		.amdhsa_private_segment_fixed_size 0
		.amdhsa_kernarg_size 432
		.amdhsa_user_sgpr_count 2
		.amdhsa_user_sgpr_dispatch_ptr 0
		.amdhsa_user_sgpr_queue_ptr 0
		.amdhsa_user_sgpr_kernarg_segment_ptr 1
		.amdhsa_user_sgpr_dispatch_id 0
		.amdhsa_user_sgpr_kernarg_preload_length 0
		.amdhsa_user_sgpr_kernarg_preload_offset 0
		.amdhsa_user_sgpr_private_segment_size 0
		.amdhsa_uses_dynamic_stack 0
		.amdhsa_enable_private_segment 0
		.amdhsa_system_sgpr_workgroup_id_x 1
		.amdhsa_system_sgpr_workgroup_id_y 0
		.amdhsa_system_sgpr_workgroup_id_z 0
		.amdhsa_system_sgpr_workgroup_info 0
		.amdhsa_system_vgpr_workitem_id 2
		.amdhsa_next_free_vgpr 248
		.amdhsa_next_free_sgpr 102
		.amdhsa_accum_offset 248
		.amdhsa_reserve_vcc 1
		.amdhsa_float_round_mode_32 0
		.amdhsa_float_round_mode_16_64 0
		.amdhsa_float_denorm_mode_32 3
		.amdhsa_float_denorm_mode_16_64 3
		.amdhsa_dx10_clamp 1
		.amdhsa_ieee_mode 1
		.amdhsa_fp16_overflow 0
		.amdhsa_tg_split 0
		.amdhsa_exception_fp_ieee_invalid_op 0
		.amdhsa_exception_fp_denorm_src 0
		.amdhsa_exception_fp_ieee_div_zero 0
		.amdhsa_exception_fp_ieee_overflow 0
		.amdhsa_exception_fp_ieee_underflow 0
		.amdhsa_exception_fp_ieee_inexact 0
		.amdhsa_exception_int_div_zero 0
	.end_amdhsa_kernel

; __global__ void __launch_bounds__(NTHREADS, 2) fwd_megakernel(Params p) {
;     extern __shared__ __attribute__((aligned(16))) unsigned char dyn_lds[];
amdhsa.kernels:
  - .agpr_count:     0
    .args:
      - .offset:         0
        .size:           176
        .value_kind:     by_value
      - .offset:         176
        .size:           4
        .value_kind:     hidden_block_count_x
      - .offset:         180
        .size:           4
        .value_kind:     hidden_block_count_y
      - .offset:         184
        .size:           4
        .value_kind:     hidden_block_count_z
      - .offset:         188
        .size:           2
        .value_kind:     hidden_group_size_x
      - .offset:         190
        .size:           2
        .value_kind:     hidden_group_size_y
      - .offset:         192
        .size:           2
        .value_kind:     hidden_group_size_z
      - .offset:         194
        .size:           2
        .value_kind:     hidden_remainder_x
      - .offset:         196
        .size:           2
        .value_kind:     hidden_remainder_y
      - .offset:         198
        .size:           2
        .value_kind:     hidden_remainder_z
      - .offset:         216
        .size:           8
        .value_kind:     hidden_global_offset_x
      - .offset:         224
        .size:           8
        .value_kind:     hidden_global_offset_y
      - .offset:         232
        .size:           8
        .value_kind:     hidden_global_offset_z
      - .offset:         240
        .size:           2
        .value_kind:     hidden_grid_dims
      - .offset:         264
        .size:           8
        .value_kind:     hidden_multigrid_sync_arg
      - .offset:         296
        .size:           4
        .value_kind:     hidden_dynamic_lds_size
    .group_segment_fixed_size: 0
    .kernarg_segment_align: 8
    .kernarg_segment_size: 432
    .language:       OpenCL C
    .language_version:
      - 2
      - 0
    .max_flat_workgroup_size: 512
    .name:           _Z14fwd_megakernel6Params
    .private_segment_fixed_size: 0
    .sgpr_count:     108
    .sgpr_spill_count: 36
    .symbol:         _Z14fwd_megakernel6Params.kd
    .uniform_work_group_size: 1
    .uses_dynamic_stack: false
    .vgpr_count:     248
    .vgpr_spill_count: 0
    .wavefront_size: 64
